# K-loops: LDS-DMA stage loads issued before the A-fragment ds_reads in each load segment
# speedup vs baseline: 1.0020x; 1.0020x over previous
; #define PG8_STAGE(bufoff, gbase, voff) do { _Pragma("unroll") for (int _i = 0; _i < 2; ++_i) \
;         __builtin_amdgcn_global_load_lds((const unsigned*)((const char*)(gbase) + (voff)[_i]), (LAS unsigned*)(lds + (bufoff) + ldsw + _i * 8192), 16, 0, 0); } while (0)
; #define PG8_LDA(dst, b, h) do { _Pragma("unroll") for (int m = 0; m < 4; ++m) _Pragma("unroll") for (int k = 0; k < 2; ++k) dst[m][k] = *(const LAS bf16x8*)(lds + PG8_SA(b, h) + aoff + m * 2048 + k * 1024); } while (0)
; #define PG8_LDB(dst, b, h) do { _Pragma("unroll") for (int n = 0; n < 2; ++n) _Pragma("unroll") for (int k = 0; k < 2; ++k) dst[n][k] = *(const LAS bf16x8*)(lds + PG8_SB(b, h) + boff + n * 2048 + k * 1024); } while (0)
; #define PG8_MMA(ai, bj, At, Bt) do { __builtin_amdgcn_s_setprio(1); _Pragma("unroll") for (int m = 0; m < 4; ++m) _Pragma("unroll") for (int n = 0; n < 2; ++n) _Pragma("unroll") for (int k = 0; k < 2; ++k) \
;         acc[ai][bj][m][n] = __builtin_amdgcn_mfma_f32_16x16x32_bf16(Bt[n][k], At[m][k], acc[ai][bj][m][n], 0, 0, 0); __builtin_amdgcn_s_setprio(0); } while (0)
; #define PG8_WAIT_V(n) asm volatile("s_waitcnt vmcnt(" #n ")" ::: "memory")
; #define PG8_WAIT_L(n) asm volatile("s_waitcnt lgkmcnt(" #n ")" ::: "memory")
; #define PG8_BAR __builtin_amdgcn_s_barrier()
; #define PG8_SCHED __builtin_amdgcn_sched_barrier(0)
; template <class Epi, class Sched, bool ALIGN_EPI = true>
; __device__ __forceinline__ void gemm_phase(LAS unsigned char* lds, const Gemm g, const Sched& S, const Epi& E) {
;     ...
;         for (int t = 0; t < nt; t += 2) {
;             const bool last = (t == nt - 2);
;             const char* a1 = cA + (size_t)(t + 1) * kstep;
;             const char* a2 = last ? nA : cA + (size_t)(t + 2) * kstep; const char* b2 = last ? nB : cB + (size_t)(t + 2) * kstep;
;             const char* a3 = a2 + kstep; const char* b3 = b2 + kstep;
;             PG8_LDB(B0, 0, 0); PG8_LDB(B1, 0, 1); PG8_SCHED; PG8_LDA(At, 0, 0); PG8_STAGE(PG8_SA(1, 1), a1 + hsA, voffA);
;             PG8_WAIT_V(8); PG8_WAIT_L(0); PG8_BAR; PG8_MMA(0, 0, At, B0); PG8_MMA(0, 1, At, B1); PG8_BAR; PG8_SCHED;
;             PG8_LDA(At, 0, 1); PG8_STAGE(PG8_SB(0, 0), b2, voffB); PG8_STAGE(PG8_SB(0, 1), b2 + hsB, voffB); PG8_STAGE(PG8_SA(0, 0), a2, voffA);
;             PG8_WAIT_V(8); PG8_WAIT_L(0); PG8_BAR; PG8_MMA(1, 0, At, B0); PG8_MMA(1, 1, At, B1); PG8_BAR; PG8_SCHED;
.LBB0_134:
	ds_read_b128 v[146:149], v158
	ds_read_b128 v[162:165], v158 offset:1024
	ds_read_b128 v[166:169], v158 offset:2048
	ds_read_b128 v[170:173], v158 offset:3072
	ds_read_b128 v[174:177], v159
	ds_read_b128 v[182:185], v159 offset:1024
	ds_read_b128 v[186:189], v159 offset:2048
	ds_read_b128 v[190:193], v159 offset:3072
	s_add_u32 s6, s4, 0xfffc0080
	s_addc_u32 s7, s5, -1
	s_cmp_eq_u32 s58, 12
	s_cselect_b32 s9, s19, s7
	s_cselect_b32 s8, s18, s6
	s_cselect_b32 s7, s3, s33
	s_cselect_b32 s6, s17, s23
	v_lshl_add_u64 v[150:151], s[4:5], 0, v[138:139]
	s_add_i32 m0, s25, 0xc000
	s_nop 0
	global_load_lds_dwordx4 v[150:151], off
	v_lshl_add_u64 v[150:151], s[4:5], 0, v[140:141]
	s_add_i32 m0, s25, 0xe000
	s_nop 0
	global_load_lds_dwordx4 v[150:151], off
	ds_read_b128 v[194:197], v160
	ds_read_b128 v[198:201], v160 offset:1024
	ds_read_b128 v[202:205], v160 offset:2048
	ds_read_b128 v[206:209], v160 offset:3072
	ds_read_b128 v[210:213], v160 offset:4096
	ds_read_b128 v[214:217], v160 offset:5120
	ds_read_b128 v[218:221], v160 offset:6144
	ds_read_b128 v[222:225], v160 offset:7168
	s_waitcnt vmcnt(8)
	s_waitcnt lgkmcnt(0)
	s_barrier
	s_setprio 1
	s_waitcnt lgkmcnt(0)
	v_mfma_f32_16x16x32_bf16 v[124:127], v[146:149], v[194:197], v[124:127]
	v_mfma_f32_16x16x32_bf16 v[120:123], v[166:169], v[194:197], v[120:123]
	v_mfma_f32_16x16x32_bf16 v[108:111], v[146:149], v[202:205], v[108:111]
	v_mfma_f32_16x16x32_bf16 v[104:107], v[166:169], v[202:205], v[104:107]
	v_mfma_f32_16x16x32_bf16 v[92:95], v[146:149], v[210:213], v[92:95]
	v_mfma_f32_16x16x32_bf16 v[88:91], v[166:169], v[210:213], v[88:91]
	v_mfma_f32_16x16x32_bf16 v[76:79], v[146:149], v[218:221], v[76:79]
	v_mfma_f32_16x16x32_bf16 v[72:75], v[166:169], v[218:221], v[72:75]
	v_mfma_f32_16x16x32_bf16 v[124:127], v[162:165], v[198:201], v[124:127]
	v_mfma_f32_16x16x32_bf16 v[120:123], v[170:173], v[198:201], v[120:123]
	v_mfma_f32_16x16x32_bf16 v[108:111], v[162:165], v[206:209], v[108:111]
	v_mfma_f32_16x16x32_bf16 v[104:107], v[170:173], v[206:209], v[104:107]
	v_mfma_f32_16x16x32_bf16 v[92:95], v[162:165], v[214:217], v[92:95]
	v_mfma_f32_16x16x32_bf16 v[88:91], v[170:173], v[214:217], v[88:91]
	v_mfma_f32_16x16x32_bf16 v[76:79], v[162:165], v[222:225], v[76:79]
	v_mfma_f32_16x16x32_bf16 v[72:75], v[170:173], v[222:225], v[72:75]
	v_mfma_f32_16x16x32_bf16 v[116:119], v[174:177], v[194:197], v[116:119]
	v_mfma_f32_16x16x32_bf16 v[112:115], v[186:189], v[194:197], v[112:115]
	v_mfma_f32_16x16x32_bf16 v[100:103], v[174:177], v[202:205], v[100:103]
	v_mfma_f32_16x16x32_bf16 v[96:99], v[186:189], v[202:205], v[96:99]
	v_mfma_f32_16x16x32_bf16 v[84:87], v[174:177], v[210:213], v[84:87]
	v_mfma_f32_16x16x32_bf16 v[80:83], v[186:189], v[210:213], v[80:83]
	v_mfma_f32_16x16x32_bf16 v[68:71], v[174:177], v[218:221], v[68:71]
	v_mfma_f32_16x16x32_bf16 v[64:67], v[186:189], v[218:221], v[64:67]
	v_mfma_f32_16x16x32_bf16 v[116:119], v[182:185], v[198:201], v[116:119]
	v_mfma_f32_16x16x32_bf16 v[112:115], v[190:193], v[198:201], v[112:115]
	v_mfma_f32_16x16x32_bf16 v[100:103], v[182:185], v[206:209], v[100:103]
	v_mfma_f32_16x16x32_bf16 v[96:99], v[190:193], v[206:209], v[96:99]
	v_mfma_f32_16x16x32_bf16 v[84:87], v[182:185], v[214:217], v[84:87]
	v_mfma_f32_16x16x32_bf16 v[80:83], v[190:193], v[214:217], v[80:83]
	v_mfma_f32_16x16x32_bf16 v[68:71], v[182:185], v[222:225], v[68:71]
	v_mfma_f32_16x16x32_bf16 v[64:67], v[190:193], v[222:225], v[64:67]
	s_setprio 0
	s_barrier
	s_add_i32 s59, s48, s24
	v_lshl_add_u64 v[150:151], s[6:7], 0, v[130:131]
	s_mov_b32 m0, s59
	s_nop 0
	global_load_lds_dwordx4 v[150:151], off
	s_add_i32 m0, s59, 0x2000
	s_add_u32 s60, s6, 0x40000
	v_lshl_add_u64 v[178:179], s[6:7], 0, v[134:135]
	s_addc_u32 s61, s7, 0
	s_add_i32 s59, s49, s24
	global_load_lds_dwordx4 v[178:179], off
	v_lshl_add_u64 v[226:227], s[60:61], 0, v[130:131]
	s_mov_b32 m0, s59
	v_lshl_add_u64 v[228:229], s[8:9], 0, v[132:133]
	global_load_lds_dwordx4 v[226:227], off
	v_lshl_add_u64 v[226:227], s[60:61], 0, v[134:135]
	s_add_i32 m0, s59, 0x2000
	s_nop 0
	global_load_lds_dwordx4 v[226:227], off
	v_lshl_add_u64 v[226:227], s[8:9], 0, v[128:129]
	s_mov_b32 m0, s25
	s_nop 0
	global_load_lds_dwordx4 v[226:227], off
	s_mov_b32 m0, s26
	s_nop 0
	global_load_lds_dwordx4 v[228:229], off
	ds_read_b128 v[194:197], v160 offset:16384
	ds_read_b128 v[198:201], v160 offset:17408
	ds_read_b128 v[202:205], v160 offset:18432
	ds_read_b128 v[206:209], v160 offset:19456
	ds_read_b128 v[210:213], v160 offset:20480
	ds_read_b128 v[214:217], v160 offset:21504
	ds_read_b128 v[218:221], v160 offset:22528
	ds_read_b128 v[222:225], v160 offset:23552
	s_waitcnt vmcnt(8)
	s_waitcnt lgkmcnt(0)
	s_barrier
; #define PG8_STAGE(bufoff, gbase, voff) do { _Pragma("unroll") for (int _i = 0; _i < 2; ++_i) \
;         __builtin_amdgcn_global_load_lds((const unsigned*)((const char*)(gbase) + (voff)[_i]), (LAS unsigned*)(lds + (bufoff) + ldsw + _i * 8192), 16, 0, 0); } while (0)
; #define PG8_LDA(dst, b, h) do { _Pragma("unroll") for (int m = 0; m < 4; ++m) _Pragma("unroll") for (int k = 0; k < 2; ++k) dst[m][k] = *(const LAS bf16x8*)(lds + PG8_SA(b, h) + aoff + m * 2048 + k * 1024); } while (0)
; #define PG8_LDB(dst, b, h) do { _Pragma("unroll") for (int n = 0; n < 2; ++n) _Pragma("unroll") for (int k = 0; k < 2; ++k) dst[n][k] = *(const LAS bf16x8*)(lds + PG8_SB(b, h) + boff + n * 2048 + k * 1024); } while (0)
; #define PG8_MMA(ai, bj, At, Bt) do { __builtin_amdgcn_s_setprio(1); _Pragma("unroll") for (int m = 0; m < 4; ++m) _Pragma("unroll") for (int n = 0; n < 2; ++n) _Pragma("unroll") for (int k = 0; k < 2; ++k) \
;         acc[ai][bj][m][n] = __builtin_amdgcn_mfma_f32_16x16x32_bf16(Bt[n][k], At[m][k], acc[ai][bj][m][n], 0, 0, 0); __builtin_amdgcn_s_setprio(0); } while (0)
; #define PG8_WAIT_V(n) asm volatile("s_waitcnt vmcnt(" #n ")" ::: "memory")
; #define PG8_WAIT_L(n) asm volatile("s_waitcnt lgkmcnt(" #n ")" ::: "memory")
; #define PG8_BAR __builtin_amdgcn_s_barrier()
; #define PG8_SCHED __builtin_amdgcn_sched_barrier(0)
; template <class Epi, class Sched, bool ALIGN_EPI = true>
; __device__ __forceinline__ void gemm_phase(LAS unsigned char* lds, const Gemm g, const Sched& S, const Epi& E) {
;     ...
;             PG8_WAIT_V(8); PG8_WAIT_L(0); PG8_BAR; PG8_MMA(1, 0, At, B0); PG8_MMA(1, 1, At, B1); PG8_BAR; PG8_SCHED;
;             PG8_LDB(B0, 1, 0); PG8_LDB(B1, 1, 1); PG8_SCHED; PG8_LDA(At, 1, 0); PG8_STAGE(PG8_SA(0, 1), a2 + hsA, voffA);
;             PG8_WAIT_V(8); PG8_WAIT_L(0); PG8_BAR; PG8_MMA(0, 0, At, B0); PG8_MMA(0, 1, At, B1); PG8_BAR; PG8_SCHED;
;             PG8_LDA(At, 1, 1); PG8_STAGE(PG8_SB(1, 0), b3, voffB); PG8_STAGE(PG8_SB(1, 1), b3 + hsB, voffB); PG8_STAGE(PG8_SA(1, 0), a3, voffA);
;             PG8_WAIT_V(8); PG8_WAIT_L(0); PG8_BAR; PG8_MMA(1, 0, At, B0); PG8_MMA(1, 1, At, B1); PG8_BAR; PG8_SCHED;
	s_setprio 1
	s_waitcnt lgkmcnt(0)
	v_mfma_f32_16x16x32_bf16 v[60:63], v[146:149], v[194:197], v[60:63]
	v_mfma_f32_16x16x32_bf16 v[56:59], v[166:169], v[194:197], v[56:59]
	v_mfma_f32_16x16x32_bf16 v[44:47], v[146:149], v[202:205], v[44:47]
	v_mfma_f32_16x16x32_bf16 v[40:43], v[166:169], v[202:205], v[40:43]
	v_mfma_f32_16x16x32_bf16 v[28:31], v[146:149], v[210:213], v[28:31]
	v_mfma_f32_16x16x32_bf16 v[24:27], v[166:169], v[210:213], v[24:27]
	v_mfma_f32_16x16x32_bf16 v[12:15], v[146:149], v[218:221], v[12:15]
	v_mfma_f32_16x16x32_bf16 v[8:11], v[166:169], v[218:221], v[8:11]
	v_mfma_f32_16x16x32_bf16 v[60:63], v[162:165], v[198:201], v[60:63]
	v_mfma_f32_16x16x32_bf16 v[56:59], v[170:173], v[198:201], v[56:59]
	v_mfma_f32_16x16x32_bf16 v[44:47], v[162:165], v[206:209], v[44:47]
	v_mfma_f32_16x16x32_bf16 v[40:43], v[170:173], v[206:209], v[40:43]
	v_mfma_f32_16x16x32_bf16 v[28:31], v[162:165], v[214:217], v[28:31]
	v_mfma_f32_16x16x32_bf16 v[24:27], v[170:173], v[214:217], v[24:27]
	v_mfma_f32_16x16x32_bf16 v[12:15], v[162:165], v[222:225], v[12:15]
	v_mfma_f32_16x16x32_bf16 v[8:11], v[170:173], v[222:225], v[8:11]
	v_mfma_f32_16x16x32_bf16 v[52:55], v[174:177], v[194:197], v[52:55]
	v_mfma_f32_16x16x32_bf16 v[48:51], v[186:189], v[194:197], v[48:51]
	v_mfma_f32_16x16x32_bf16 v[36:39], v[174:177], v[202:205], v[36:39]
	v_mfma_f32_16x16x32_bf16 v[32:35], v[186:189], v[202:205], v[32:35]
	v_mfma_f32_16x16x32_bf16 v[20:23], v[174:177], v[210:213], v[20:23]
	v_mfma_f32_16x16x32_bf16 v[16:19], v[186:189], v[210:213], v[16:19]
	v_mfma_f32_16x16x32_bf16 v[4:7], v[174:177], v[218:221], v[4:7]
	v_mfma_f32_16x16x32_bf16 v[0:3], v[186:189], v[218:221], v[0:3]
	v_mfma_f32_16x16x32_bf16 v[52:55], v[182:185], v[198:201], v[52:55]
	v_mfma_f32_16x16x32_bf16 v[48:51], v[190:193], v[198:201], v[48:51]
	v_mfma_f32_16x16x32_bf16 v[36:39], v[182:185], v[206:209], v[36:39]
	v_mfma_f32_16x16x32_bf16 v[32:35], v[190:193], v[206:209], v[32:35]
	v_mfma_f32_16x16x32_bf16 v[20:23], v[182:185], v[214:217], v[20:23]
	v_mfma_f32_16x16x32_bf16 v[16:19], v[190:193], v[214:217], v[16:19]
	v_mfma_f32_16x16x32_bf16 v[4:7], v[182:185], v[222:225], v[4:7]
	v_mfma_f32_16x16x32_bf16 v[0:3], v[190:193], v[222:225], v[0:3]
	s_setprio 0
	s_barrier
	s_add_i32 s59, 0, 0x18000
	v_add_u32_e32 v136, s59, v156
	s_add_i32 s60, 0, 0x1c000
	ds_read_b128 v[146:149], v136
	ds_read_b128 v[162:165], v136 offset:1024
	ds_read_b128 v[166:169], v136 offset:2048
	ds_read_b128 v[170:173], v136 offset:3072
	v_add_u32_e32 v136, s60, v156
	ds_read_b128 v[174:177], v136
	ds_read_b128 v[182:185], v136 offset:1024
	ds_read_b128 v[186:189], v136 offset:2048
	ds_read_b128 v[190:193], v136 offset:3072
	s_add_u32 s8, s8, 0x40000
	s_addc_u32 s9, s9, 0
	s_mov_b32 m0, s27
	v_lshl_add_u64 v[230:231], s[8:9], 0, v[128:129]
	global_load_lds_dwordx4 v[230:231], off
	v_lshl_add_u64 v[230:231], s[8:9], 0, v[132:133]
	s_mov_b32 m0, s28
	s_nop 0
	global_load_lds_dwordx4 v[230:231], off
	ds_read_b128 v[194:197], v160 offset:32768
	ds_read_b128 v[198:201], v160 offset:33792
	ds_read_b128 v[202:205], v160 offset:34816
	ds_read_b128 v[206:209], v160 offset:35840
	ds_read_b128 v[210:213], v160 offset:36864
	ds_read_b128 v[214:217], v160 offset:37888
	ds_read_b128 v[218:221], v160 offset:38912
	ds_read_b128 v[222:225], v160 offset:39936
	s_waitcnt vmcnt(8)
	s_waitcnt lgkmcnt(0)
	s_barrier
	s_setprio 1
	s_waitcnt lgkmcnt(0)
	v_mfma_f32_16x16x32_bf16 v[124:127], v[146:149], v[194:197], v[124:127]
	v_mfma_f32_16x16x32_bf16 v[120:123], v[166:169], v[194:197], v[120:123]
	v_mfma_f32_16x16x32_bf16 v[108:111], v[146:149], v[202:205], v[108:111]
	v_mfma_f32_16x16x32_bf16 v[104:107], v[166:169], v[202:205], v[104:107]
	v_mfma_f32_16x16x32_bf16 v[92:95], v[146:149], v[210:213], v[92:95]
	v_mfma_f32_16x16x32_bf16 v[88:91], v[166:169], v[210:213], v[88:91]
	v_mfma_f32_16x16x32_bf16 v[76:79], v[146:149], v[218:221], v[76:79]
	v_mfma_f32_16x16x32_bf16 v[72:75], v[166:169], v[218:221], v[72:75]
	v_mfma_f32_16x16x32_bf16 v[124:127], v[162:165], v[198:201], v[124:127]
	v_mfma_f32_16x16x32_bf16 v[120:123], v[170:173], v[198:201], v[120:123]
	v_mfma_f32_16x16x32_bf16 v[108:111], v[162:165], v[206:209], v[108:111]
	v_mfma_f32_16x16x32_bf16 v[104:107], v[170:173], v[206:209], v[104:107]
	v_mfma_f32_16x16x32_bf16 v[92:95], v[162:165], v[214:217], v[92:95]
	v_mfma_f32_16x16x32_bf16 v[88:91], v[170:173], v[214:217], v[88:91]
	v_mfma_f32_16x16x32_bf16 v[76:79], v[162:165], v[222:225], v[76:79]
	v_mfma_f32_16x16x32_bf16 v[72:75], v[170:173], v[222:225], v[72:75]
	v_mfma_f32_16x16x32_bf16 v[116:119], v[174:177], v[194:197], v[116:119]
	v_mfma_f32_16x16x32_bf16 v[112:115], v[186:189], v[194:197], v[112:115]
	v_mfma_f32_16x16x32_bf16 v[100:103], v[174:177], v[202:205], v[100:103]
	v_mfma_f32_16x16x32_bf16 v[96:99], v[186:189], v[202:205], v[96:99]
	v_mfma_f32_16x16x32_bf16 v[84:87], v[174:177], v[210:213], v[84:87]
	v_mfma_f32_16x16x32_bf16 v[80:83], v[186:189], v[210:213], v[80:83]
	v_mfma_f32_16x16x32_bf16 v[68:71], v[174:177], v[218:221], v[68:71]
	v_mfma_f32_16x16x32_bf16 v[64:67], v[186:189], v[218:221], v[64:67]
	v_mfma_f32_16x16x32_bf16 v[116:119], v[182:185], v[198:201], v[116:119]
	v_mfma_f32_16x16x32_bf16 v[112:115], v[190:193], v[198:201], v[112:115]
	v_mfma_f32_16x16x32_bf16 v[100:103], v[182:185], v[206:209], v[100:103]
	v_mfma_f32_16x16x32_bf16 v[96:99], v[190:193], v[206:209], v[96:99]
	v_mfma_f32_16x16x32_bf16 v[84:87], v[182:185], v[214:217], v[84:87]
	v_mfma_f32_16x16x32_bf16 v[80:83], v[190:193], v[214:217], v[80:83]
	v_mfma_f32_16x16x32_bf16 v[68:71], v[182:185], v[222:225], v[68:71]
	v_mfma_f32_16x16x32_bf16 v[64:67], v[190:193], v[222:225], v[64:67]
	s_setprio 0
	s_barrier
; #define PG8_STAGE(bufoff, gbase, voff) do { _Pragma("unroll") for (int _i = 0; _i < 2; ++_i) \
;         __builtin_amdgcn_global_load_lds((const unsigned*)((const char*)(gbase) + (voff)[_i]), (LAS unsigned*)(lds + (bufoff) + ldsw + _i * 8192), 16, 0, 0); } while (0)
; #define PG8_LDA(dst, b, h) do { _Pragma("unroll") for (int m = 0; m < 4; ++m) _Pragma("unroll") for (int k = 0; k < 2; ++k) dst[m][k] = *(const LAS bf16x8*)(lds + PG8_SA(b, h) + aoff + m * 2048 + k * 1024); } while (0)
; #define PG8_MMA(ai, bj, At, Bt) do { __builtin_amdgcn_s_setprio(1); _Pragma("unroll") for (int m = 0; m < 4; ++m) _Pragma("unroll") for (int n = 0; n < 2; ++n) _Pragma("unroll") for (int k = 0; k < 2; ++k) \
;         acc[ai][bj][m][n] = __builtin_amdgcn_mfma_f32_16x16x32_bf16(Bt[n][k], At[m][k], acc[ai][bj][m][n], 0, 0, 0); __builtin_amdgcn_s_setprio(0); } while (0)
; #define PG8_WAIT_V(n) asm volatile("s_waitcnt vmcnt(" #n ")" ::: "memory")
; #define PG8_WAIT_L(n) asm volatile("s_waitcnt lgkmcnt(" #n ")" ::: "memory")
; #define PG8_BAR __builtin_amdgcn_s_barrier()
; #define PG8_SCHED __builtin_amdgcn_sched_barrier(0)
; template <class Epi, class Sched, bool ALIGN_EPI = true>
; __device__ __forceinline__ void gemm_phase(LAS unsigned char* lds, const Gemm g, const Sched& S, const Epi& E) {
;     ...
;             PG8_LDA(At, 1, 1); PG8_STAGE(PG8_SB(1, 0), b3, voffB); PG8_STAGE(PG8_SB(1, 1), b3 + hsB, voffB); PG8_STAGE(PG8_SA(1, 0), a3, voffA);
;             PG8_WAIT_V(8); PG8_WAIT_L(0); PG8_BAR; PG8_MMA(1, 0, At, B0); PG8_MMA(1, 1, At, B1); PG8_BAR; PG8_SCHED;
;         }
	s_add_i32 s8, s59, s24
	v_lshl_add_u64 v[150:151], v[150:151], 0, s[12:13]
	s_mov_b32 m0, s8
	s_nop 0
	global_load_lds_dwordx4 v[150:151], off
	s_add_i32 m0, s8, 0x2000
	s_add_u32 s6, s6, 0x40080
	v_lshl_add_u64 v[150:151], v[178:179], 0, s[12:13]
	s_addc_u32 s7, s7, 0
	s_add_i32 s8, s60, s24
	global_load_lds_dwordx4 v[150:151], off
	v_lshl_add_u64 v[150:151], s[6:7], 0, v[130:131]
	s_mov_b32 m0, s8
	s_nop 0
	global_load_lds_dwordx4 v[150:151], off
	v_lshl_add_u64 v[150:151], s[6:7], 0, v[134:135]
	s_add_i32 m0, s8, 0x2000
	s_nop 0
	global_load_lds_dwordx4 v[150:151], off
	v_lshl_add_u64 v[150:151], v[226:227], 0, s[12:13]
	s_mov_b32 m0, s31
	s_nop 0
	global_load_lds_dwordx4 v[150:151], off
	v_lshl_add_u64 v[150:151], v[228:229], 0, s[12:13]
	s_mov_b32 m0, s34
	s_nop 0
	global_load_lds_dwordx4 v[150:151], off
	ds_read_b128 v[194:197], v160 offset:49152
	ds_read_b128 v[198:201], v160 offset:50176
	ds_read_b128 v[202:205], v160 offset:51200
	ds_read_b128 v[206:209], v160 offset:52224
	ds_read_b128 v[210:213], v160 offset:53248
	ds_read_b128 v[214:217], v160 offset:54272
	ds_read_b128 v[218:221], v160 offset:55296
	ds_read_b128 v[222:225], v160 offset:56320
	s_waitcnt vmcnt(8)
	s_waitcnt lgkmcnt(0)
	s_barrier
	s_setprio 1
	s_waitcnt lgkmcnt(0)
	v_mfma_f32_16x16x32_bf16 v[60:63], v[146:149], v[194:197], v[60:63]
	v_mfma_f32_16x16x32_bf16 v[56:59], v[166:169], v[194:197], v[56:59]
	v_mfma_f32_16x16x32_bf16 v[44:47], v[146:149], v[202:205], v[44:47]
	v_mfma_f32_16x16x32_bf16 v[40:43], v[166:169], v[202:205], v[40:43]
	v_mfma_f32_16x16x32_bf16 v[28:31], v[146:149], v[210:213], v[28:31]
	v_mfma_f32_16x16x32_bf16 v[24:27], v[166:169], v[210:213], v[24:27]
	v_mfma_f32_16x16x32_bf16 v[12:15], v[146:149], v[218:221], v[12:15]
	v_mfma_f32_16x16x32_bf16 v[8:11], v[166:169], v[218:221], v[8:11]
	v_mfma_f32_16x16x32_bf16 v[60:63], v[162:165], v[198:201], v[60:63]
	v_mfma_f32_16x16x32_bf16 v[56:59], v[170:173], v[198:201], v[56:59]
	v_mfma_f32_16x16x32_bf16 v[44:47], v[162:165], v[206:209], v[44:47]
	v_mfma_f32_16x16x32_bf16 v[40:43], v[170:173], v[206:209], v[40:43]
	v_mfma_f32_16x16x32_bf16 v[28:31], v[162:165], v[214:217], v[28:31]
	v_mfma_f32_16x16x32_bf16 v[24:27], v[170:173], v[214:217], v[24:27]
	v_mfma_f32_16x16x32_bf16 v[12:15], v[162:165], v[222:225], v[12:15]
	v_mfma_f32_16x16x32_bf16 v[8:11], v[170:173], v[222:225], v[8:11]
	v_mfma_f32_16x16x32_bf16 v[52:55], v[174:177], v[194:197], v[52:55]
	v_mfma_f32_16x16x32_bf16 v[48:51], v[186:189], v[194:197], v[48:51]
	v_mfma_f32_16x16x32_bf16 v[36:39], v[174:177], v[202:205], v[36:39]
	v_mfma_f32_16x16x32_bf16 v[32:35], v[186:189], v[202:205], v[32:35]
	v_mfma_f32_16x16x32_bf16 v[20:23], v[174:177], v[210:213], v[20:23]
	v_mfma_f32_16x16x32_bf16 v[16:19], v[186:189], v[210:213], v[16:19]
	v_mfma_f32_16x16x32_bf16 v[4:7], v[174:177], v[218:221], v[4:7]
	v_mfma_f32_16x16x32_bf16 v[0:3], v[186:189], v[218:221], v[0:3]
	v_mfma_f32_16x16x32_bf16 v[52:55], v[182:185], v[198:201], v[52:55]
	v_mfma_f32_16x16x32_bf16 v[48:51], v[190:193], v[198:201], v[48:51]
	v_mfma_f32_16x16x32_bf16 v[36:39], v[182:185], v[206:209], v[36:39]
	v_mfma_f32_16x16x32_bf16 v[32:35], v[190:193], v[206:209], v[32:35]
	v_mfma_f32_16x16x32_bf16 v[20:23], v[182:185], v[214:217], v[20:23]
	v_mfma_f32_16x16x32_bf16 v[16:19], v[190:193], v[214:217], v[16:19]
	v_mfma_f32_16x16x32_bf16 v[4:7], v[182:185], v[222:225], v[4:7]
	v_mfma_f32_16x16x32_bf16 v[0:3], v[190:193], v[222:225], v[0:3]
	s_setprio 0
	s_barrier
	s_add_i32 s58, s58, 2
	s_add_u32 s4, s4, 0x100
	s_addc_u32 s5, s5, 0
	s_add_u32 s23, s23, 0x100
	s_addc_u32 s33, s33, 0
	s_cmp_gt_u32 s58, 13
	s_cbranch_scc0 .LBB0_134
	s_and_b64 vcc, exec, s[14:15]
	s_cbranch_vccz .LBB0_137
	s_barrier

; #define PG8_STAGE(bufoff, gbase, voff) do { _Pragma("unroll") for (int _i = 0; _i < 2; ++_i) \
;         __builtin_amdgcn_global_load_lds((const unsigned*)((const char*)(gbase) + (voff)[_i]), (LAS unsigned*)(lds + (bufoff) + ldsw + _i * 8192), 16, 0, 0); } while (0)
; #define PG8_LDA(dst, b, h) do { _Pragma("unroll") for (int m = 0; m < 4; ++m) _Pragma("unroll") for (int k = 0; k < 2; ++k) dst[m][k] = *(const LAS bf16x8*)(lds + PG8_SA(b, h) + aoff + m * 2048 + k * 1024); } while (0)
; #define PG8_LDB(dst, b, h) do { _Pragma("unroll") for (int n = 0; n < 2; ++n) _Pragma("unroll") for (int k = 0; k < 2; ++k) dst[n][k] = *(const LAS bf16x8*)(lds + PG8_SB(b, h) + boff + n * 2048 + k * 1024); } while (0)
; #define PG8_MMA(ai, bj, At, Bt) do { __builtin_amdgcn_s_setprio(1); _Pragma("unroll") for (int m = 0; m < 4; ++m) _Pragma("unroll") for (int n = 0; n < 2; ++n) _Pragma("unroll") for (int k = 0; k < 2; ++k) \
;         acc[ai][bj][m][n] = __builtin_amdgcn_mfma_f32_16x16x32_bf16(Bt[n][k], At[m][k], acc[ai][bj][m][n], 0, 0, 0); __builtin_amdgcn_s_setprio(0); } while (0)
; #define PG8_WAIT_V(n) asm volatile("s_waitcnt vmcnt(" #n ")" ::: "memory")
; #define PG8_WAIT_L(n) asm volatile("s_waitcnt lgkmcnt(" #n ")" ::: "memory")
; #define PG8_BAR __builtin_amdgcn_s_barrier()
; #define PG8_SCHED __builtin_amdgcn_sched_barrier(0)
; template <class Epi, class Sched, bool ALIGN_EPI = true>
; __device__ __forceinline__ void gemm_phase(LAS unsigned char* lds, const Gemm g, const Sched& S, const Epi& E) {
;     ...
;         for (int t = 0; t < nt; t += 2) {
;             const bool last = (t == nt - 2);
;             const char* a1 = cA + (size_t)(t + 1) * kstep;
;             const char* a2 = last ? nA : cA + (size_t)(t + 2) * kstep; const char* b2 = last ? nB : cB + (size_t)(t + 2) * kstep;
;             const char* a3 = a2 + kstep; const char* b3 = b2 + kstep;
;             PG8_LDB(B0, 0, 0); PG8_LDB(B1, 0, 1); PG8_SCHED; PG8_LDA(At, 0, 0); PG8_STAGE(PG8_SA(1, 1), a1 + hsA, voffA);
;             PG8_WAIT_V(8); PG8_WAIT_L(0); PG8_BAR; PG8_MMA(0, 0, At, B0); PG8_MMA(0, 1, At, B1); PG8_BAR; PG8_SCHED;
;             PG8_LDA(At, 0, 1); PG8_STAGE(PG8_SB(0, 0), b2, voffB); PG8_STAGE(PG8_SB(0, 1), b2 + hsB, voffB); PG8_STAGE(PG8_SA(0, 0), a2, voffA);
;             PG8_WAIT_V(8); PG8_WAIT_L(0); PG8_BAR; PG8_MMA(1, 0, At, B0); PG8_MMA(1, 1, At, B1); PG8_BAR; PG8_SCHED;
.LBB0_704:
	ds_read_b128 v[144:147], v156
	ds_read_b128 v[148:151], v156 offset:1024
	ds_read_b128 v[160:163], v156 offset:2048
	ds_read_b128 v[164:167], v156 offset:3072
	ds_read_b128 v[168:171], v157
	ds_read_b128 v[172:175], v157 offset:1024
	ds_read_b128 v[176:179], v157 offset:2048
	ds_read_b128 v[182:185], v157 offset:3072
	s_add_u32 s38, s36, 0xfff80080
	s_addc_u32 s39, s37, -1
	s_cmp_eq_u32 s57, 28
	s_cselect_b32 s41, s9, s39
	s_cselect_b32 s40, s27, s38
	s_cselect_b32 s39, s25, s56
	s_cselect_b32 s38, s35, s55
	v_lshl_add_u64 v[218:219], s[36:37], 0, v[136:137]
	s_add_i32 m0, s42, 0xc000
	s_nop 0
	global_load_lds_dwordx4 v[218:219], off
	v_lshl_add_u64 v[218:219], s[36:37], 0, v[138:139]
	s_add_i32 m0, s42, 0xe000
	s_nop 0
	global_load_lds_dwordx4 v[218:219], off
	ds_read_b128 v[186:189], v158
	ds_read_b128 v[190:193], v158 offset:1024
	ds_read_b128 v[194:197], v158 offset:2048
	ds_read_b128 v[198:201], v158 offset:3072
	ds_read_b128 v[202:205], v158 offset:4096
	ds_read_b128 v[206:209], v158 offset:5120
	ds_read_b128 v[210:213], v158 offset:6144
	ds_read_b128 v[214:217], v158 offset:7168
	s_waitcnt vmcnt(8)
	s_waitcnt lgkmcnt(0)
	s_barrier
	s_setprio 1
	s_waitcnt lgkmcnt(0)
	v_mfma_f32_16x16x32_bf16 v[124:127], v[144:147], v[186:189], v[124:127]
	v_mfma_f32_16x16x32_bf16 v[120:123], v[160:163], v[186:189], v[120:123]
	v_mfma_f32_16x16x32_bf16 v[112:115], v[144:147], v[194:197], v[112:115]
	v_mfma_f32_16x16x32_bf16 v[104:107], v[160:163], v[194:197], v[104:107]
	v_mfma_f32_16x16x32_bf16 v[96:99], v[144:147], v[202:205], v[96:99]
	v_mfma_f32_16x16x32_bf16 v[88:91], v[160:163], v[202:205], v[88:91]
	v_mfma_f32_16x16x32_bf16 v[80:83], v[144:147], v[210:213], v[80:83]
	v_mfma_f32_16x16x32_bf16 v[72:75], v[160:163], v[210:213], v[72:75]
	v_mfma_f32_16x16x32_bf16 v[124:127], v[148:151], v[190:193], v[124:127]
	v_mfma_f32_16x16x32_bf16 v[120:123], v[164:167], v[190:193], v[120:123]
	v_mfma_f32_16x16x32_bf16 v[112:115], v[148:151], v[198:201], v[112:115]
	v_mfma_f32_16x16x32_bf16 v[104:107], v[164:167], v[198:201], v[104:107]
	v_mfma_f32_16x16x32_bf16 v[96:99], v[148:151], v[206:209], v[96:99]
	v_mfma_f32_16x16x32_bf16 v[88:91], v[164:167], v[206:209], v[88:91]
	v_mfma_f32_16x16x32_bf16 v[80:83], v[148:151], v[214:217], v[80:83]
	v_mfma_f32_16x16x32_bf16 v[72:75], v[164:167], v[214:217], v[72:75]
	v_mfma_f32_16x16x32_bf16 v[116:119], v[168:171], v[186:189], v[116:119]
	v_mfma_f32_16x16x32_bf16 v[108:111], v[176:179], v[186:189], v[108:111]
	v_mfma_f32_16x16x32_bf16 v[100:103], v[168:171], v[194:197], v[100:103]
	v_mfma_f32_16x16x32_bf16 v[92:95], v[176:179], v[194:197], v[92:95]
	v_mfma_f32_16x16x32_bf16 v[84:87], v[168:171], v[202:205], v[84:87]
	v_mfma_f32_16x16x32_bf16 v[76:79], v[176:179], v[202:205], v[76:79]
	v_mfma_f32_16x16x32_bf16 v[68:71], v[168:171], v[210:213], v[68:71]
	v_mfma_f32_16x16x32_bf16 v[64:67], v[176:179], v[210:213], v[64:67]
	v_mfma_f32_16x16x32_bf16 v[116:119], v[172:175], v[190:193], v[116:119]
	v_mfma_f32_16x16x32_bf16 v[108:111], v[182:185], v[190:193], v[108:111]
	v_mfma_f32_16x16x32_bf16 v[100:103], v[172:175], v[198:201], v[100:103]
	v_mfma_f32_16x16x32_bf16 v[92:95], v[182:185], v[198:201], v[92:95]
	v_mfma_f32_16x16x32_bf16 v[84:87], v[172:175], v[206:209], v[84:87]
	v_mfma_f32_16x16x32_bf16 v[76:79], v[182:185], v[206:209], v[76:79]
	v_mfma_f32_16x16x32_bf16 v[68:71], v[172:175], v[214:217], v[68:71]
	v_mfma_f32_16x16x32_bf16 v[64:67], v[182:185], v[214:217], v[64:67]
	s_setprio 0
	s_barrier
	s_add_i32 s58, s53, s33
	v_lshl_add_u64 v[218:219], s[38:39], 0, v[130:131]
	s_mov_b32 m0, s58
	s_nop 0
	global_load_lds_dwordx4 v[218:219], off
	s_add_i32 m0, s58, 0x2000
	s_add_u32 s58, s38, 0x80000
	v_lshl_add_u64 v[220:221], s[38:39], 0, v[134:135]
	s_addc_u32 s59, s39, 0
	s_add_i32 s60, s54, s33
	global_load_lds_dwordx4 v[220:221], off
	v_lshl_add_u64 v[222:223], s[58:59], 0, v[130:131]
	s_mov_b32 m0, s60
	v_lshl_add_u64 v[224:225], s[40:41], 0, v[132:133]
	global_load_lds_dwordx4 v[222:223], off
	v_lshl_add_u64 v[222:223], s[58:59], 0, v[134:135]
	s_add_i32 m0, s60, 0x2000
	s_nop 0
	global_load_lds_dwordx4 v[222:223], off
	v_lshl_add_u64 v[222:223], s[40:41], 0, v[128:129]
	s_mov_b32 m0, s42
	s_nop 0
	global_load_lds_dwordx4 v[222:223], off
	s_mov_b32 m0, s43
	s_nop 0
	global_load_lds_dwordx4 v[224:225], off
	ds_read_b128 v[186:189], v158 offset:16384
	ds_read_b128 v[190:193], v158 offset:17408
	ds_read_b128 v[194:197], v158 offset:18432
	ds_read_b128 v[198:201], v158 offset:19456
	ds_read_b128 v[202:205], v158 offset:20480
	ds_read_b128 v[206:209], v158 offset:21504
	ds_read_b128 v[210:213], v158 offset:22528
	ds_read_b128 v[214:217], v158 offset:23552
	s_waitcnt vmcnt(8)
	s_waitcnt lgkmcnt(0)
	s_barrier
; #define PG8_STAGE(bufoff, gbase, voff) do { _Pragma("unroll") for (int _i = 0; _i < 2; ++_i) \
;         __builtin_amdgcn_global_load_lds((const unsigned*)((const char*)(gbase) + (voff)[_i]), (LAS unsigned*)(lds + (bufoff) + ldsw + _i * 8192), 16, 0, 0); } while (0)
; #define PG8_LDA(dst, b, h) do { _Pragma("unroll") for (int m = 0; m < 4; ++m) _Pragma("unroll") for (int k = 0; k < 2; ++k) dst[m][k] = *(const LAS bf16x8*)(lds + PG8_SA(b, h) + aoff + m * 2048 + k * 1024); } while (0)
; #define PG8_LDB(dst, b, h) do { _Pragma("unroll") for (int n = 0; n < 2; ++n) _Pragma("unroll") for (int k = 0; k < 2; ++k) dst[n][k] = *(const LAS bf16x8*)(lds + PG8_SB(b, h) + boff + n * 2048 + k * 1024); } while (0)
; #define PG8_MMA(ai, bj, At, Bt) do { __builtin_amdgcn_s_setprio(1); _Pragma("unroll") for (int m = 0; m < 4; ++m) _Pragma("unroll") for (int n = 0; n < 2; ++n) _Pragma("unroll") for (int k = 0; k < 2; ++k) \
;         acc[ai][bj][m][n] = __builtin_amdgcn_mfma_f32_16x16x32_bf16(Bt[n][k], At[m][k], acc[ai][bj][m][n], 0, 0, 0); __builtin_amdgcn_s_setprio(0); } while (0)
; #define PG8_WAIT_V(n) asm volatile("s_waitcnt vmcnt(" #n ")" ::: "memory")
; #define PG8_WAIT_L(n) asm volatile("s_waitcnt lgkmcnt(" #n ")" ::: "memory")
; #define PG8_BAR __builtin_amdgcn_s_barrier()
; #define PG8_SCHED __builtin_amdgcn_sched_barrier(0)
; template <class Epi, class Sched, bool ALIGN_EPI = true>
; __device__ __forceinline__ void gemm_phase(LAS unsigned char* lds, const Gemm g, const Sched& S, const Epi& E) {
;     ...
;             PG8_WAIT_V(8); PG8_WAIT_L(0); PG8_BAR; PG8_MMA(1, 0, At, B0); PG8_MMA(1, 1, At, B1); PG8_BAR; PG8_SCHED;
;             PG8_LDB(B0, 1, 0); PG8_LDB(B1, 1, 1); PG8_SCHED; PG8_LDA(At, 1, 0); PG8_STAGE(PG8_SA(0, 1), a2 + hsA, voffA);
;             PG8_WAIT_V(8); PG8_WAIT_L(0); PG8_BAR; PG8_MMA(0, 0, At, B0); PG8_MMA(0, 1, At, B1); PG8_BAR; PG8_SCHED;
;             PG8_LDA(At, 1, 1); PG8_STAGE(PG8_SB(1, 0), b3, voffB); PG8_STAGE(PG8_SB(1, 1), b3 + hsB, voffB); PG8_STAGE(PG8_SA(1, 0), a3, voffA);
;             PG8_WAIT_V(8); PG8_WAIT_L(0); PG8_BAR; PG8_MMA(1, 0, At, B0); PG8_MMA(1, 1, At, B1); PG8_BAR; PG8_SCHED;
	s_setprio 1
	s_waitcnt lgkmcnt(0)
	v_mfma_f32_16x16x32_bf16 v[60:63], v[144:147], v[186:189], v[60:63]
	v_mfma_f32_16x16x32_bf16 v[56:59], v[160:163], v[186:189], v[56:59]
	v_mfma_f32_16x16x32_bf16 v[48:51], v[144:147], v[194:197], v[48:51]
	v_mfma_f32_16x16x32_bf16 v[40:43], v[160:163], v[194:197], v[40:43]
	v_mfma_f32_16x16x32_bf16 v[32:35], v[144:147], v[202:205], v[32:35]
	v_mfma_f32_16x16x32_bf16 v[24:27], v[160:163], v[202:205], v[24:27]
	v_mfma_f32_16x16x32_bf16 v[16:19], v[144:147], v[210:213], v[16:19]
	v_mfma_f32_16x16x32_bf16 v[8:11], v[160:163], v[210:213], v[8:11]
	v_mfma_f32_16x16x32_bf16 v[60:63], v[148:151], v[190:193], v[60:63]
	v_mfma_f32_16x16x32_bf16 v[56:59], v[164:167], v[190:193], v[56:59]
	v_mfma_f32_16x16x32_bf16 v[48:51], v[148:151], v[198:201], v[48:51]
	v_mfma_f32_16x16x32_bf16 v[40:43], v[164:167], v[198:201], v[40:43]
	v_mfma_f32_16x16x32_bf16 v[32:35], v[148:151], v[206:209], v[32:35]
	v_mfma_f32_16x16x32_bf16 v[24:27], v[164:167], v[206:209], v[24:27]
	v_mfma_f32_16x16x32_bf16 v[16:19], v[148:151], v[214:217], v[16:19]
	v_mfma_f32_16x16x32_bf16 v[8:11], v[164:167], v[214:217], v[8:11]
	v_mfma_f32_16x16x32_bf16 v[52:55], v[168:171], v[186:189], v[52:55]
	v_mfma_f32_16x16x32_bf16 v[44:47], v[176:179], v[186:189], v[44:47]
	v_mfma_f32_16x16x32_bf16 v[36:39], v[168:171], v[194:197], v[36:39]
	v_mfma_f32_16x16x32_bf16 v[28:31], v[176:179], v[194:197], v[28:31]
	v_mfma_f32_16x16x32_bf16 v[20:23], v[168:171], v[202:205], v[20:23]
	v_mfma_f32_16x16x32_bf16 v[12:15], v[176:179], v[202:205], v[12:15]
	v_mfma_f32_16x16x32_bf16 v[4:7], v[168:171], v[210:213], v[4:7]
	v_mfma_f32_16x16x32_bf16 v[0:3], v[176:179], v[210:213], v[0:3]
	v_mfma_f32_16x16x32_bf16 v[52:55], v[172:175], v[190:193], v[52:55]
	v_mfma_f32_16x16x32_bf16 v[44:47], v[182:185], v[190:193], v[44:47]
	v_mfma_f32_16x16x32_bf16 v[36:39], v[172:175], v[198:201], v[36:39]
	v_mfma_f32_16x16x32_bf16 v[28:31], v[182:185], v[198:201], v[28:31]
	v_mfma_f32_16x16x32_bf16 v[20:23], v[172:175], v[206:209], v[20:23]
	v_mfma_f32_16x16x32_bf16 v[12:15], v[182:185], v[206:209], v[12:15]
	v_mfma_f32_16x16x32_bf16 v[4:7], v[172:175], v[214:217], v[4:7]
	v_mfma_f32_16x16x32_bf16 v[0:3], v[182:185], v[214:217], v[0:3]
	s_setprio 0
	s_barrier
	s_add_i32 s58, 0, 0x18000
	v_add_u32_e32 v159, s58, v154
	s_add_i32 s59, 0, 0x1c000
	ds_read_b128 v[144:147], v159
	ds_read_b128 v[148:151], v159 offset:1024
	ds_read_b128 v[160:163], v159 offset:2048
	ds_read_b128 v[164:167], v159 offset:3072
	v_add_u32_e32 v159, s59, v154
	ds_read_b128 v[168:171], v159
	ds_read_b128 v[172:175], v159 offset:1024
	ds_read_b128 v[176:179], v159 offset:2048
	ds_read_b128 v[182:185], v159 offset:3072
	s_add_u32 s40, s40, 0x80000
	s_addc_u32 s41, s41, 0
	s_mov_b32 m0, s44
	v_lshl_add_u64 v[226:227], s[40:41], 0, v[128:129]
	global_load_lds_dwordx4 v[226:227], off
	v_lshl_add_u64 v[226:227], s[40:41], 0, v[132:133]
	s_mov_b32 m0, s45
	s_nop 0
	global_load_lds_dwordx4 v[226:227], off
	ds_read_b128 v[186:189], v158 offset:32768
	ds_read_b128 v[190:193], v158 offset:33792
	ds_read_b128 v[194:197], v158 offset:34816
	ds_read_b128 v[198:201], v158 offset:35840
	ds_read_b128 v[202:205], v158 offset:36864
	ds_read_b128 v[206:209], v158 offset:37888
	ds_read_b128 v[210:213], v158 offset:38912
	ds_read_b128 v[214:217], v158 offset:39936
	s_waitcnt vmcnt(8)
	s_waitcnt lgkmcnt(0)
	s_barrier
	s_setprio 1
	s_waitcnt lgkmcnt(0)
	v_mfma_f32_16x16x32_bf16 v[124:127], v[144:147], v[186:189], v[124:127]
	v_mfma_f32_16x16x32_bf16 v[120:123], v[160:163], v[186:189], v[120:123]
	v_mfma_f32_16x16x32_bf16 v[112:115], v[144:147], v[194:197], v[112:115]
	v_mfma_f32_16x16x32_bf16 v[104:107], v[160:163], v[194:197], v[104:107]
	v_mfma_f32_16x16x32_bf16 v[96:99], v[144:147], v[202:205], v[96:99]
	v_mfma_f32_16x16x32_bf16 v[88:91], v[160:163], v[202:205], v[88:91]
	v_mfma_f32_16x16x32_bf16 v[80:83], v[144:147], v[210:213], v[80:83]
	v_mfma_f32_16x16x32_bf16 v[72:75], v[160:163], v[210:213], v[72:75]
	v_mfma_f32_16x16x32_bf16 v[124:127], v[148:151], v[190:193], v[124:127]
	v_mfma_f32_16x16x32_bf16 v[120:123], v[164:167], v[190:193], v[120:123]
	v_mfma_f32_16x16x32_bf16 v[112:115], v[148:151], v[198:201], v[112:115]
	v_mfma_f32_16x16x32_bf16 v[104:107], v[164:167], v[198:201], v[104:107]
	v_mfma_f32_16x16x32_bf16 v[96:99], v[148:151], v[206:209], v[96:99]
	v_mfma_f32_16x16x32_bf16 v[88:91], v[164:167], v[206:209], v[88:91]
	v_mfma_f32_16x16x32_bf16 v[80:83], v[148:151], v[214:217], v[80:83]
	v_mfma_f32_16x16x32_bf16 v[72:75], v[164:167], v[214:217], v[72:75]
	v_mfma_f32_16x16x32_bf16 v[116:119], v[168:171], v[186:189], v[116:119]
	v_mfma_f32_16x16x32_bf16 v[108:111], v[176:179], v[186:189], v[108:111]
	v_mfma_f32_16x16x32_bf16 v[100:103], v[168:171], v[194:197], v[100:103]
	v_mfma_f32_16x16x32_bf16 v[92:95], v[176:179], v[194:197], v[92:95]
	v_mfma_f32_16x16x32_bf16 v[84:87], v[168:171], v[202:205], v[84:87]
	v_mfma_f32_16x16x32_bf16 v[76:79], v[176:179], v[202:205], v[76:79]
	v_mfma_f32_16x16x32_bf16 v[68:71], v[168:171], v[210:213], v[68:71]
	v_mfma_f32_16x16x32_bf16 v[64:67], v[176:179], v[210:213], v[64:67]
	v_mfma_f32_16x16x32_bf16 v[116:119], v[172:175], v[190:193], v[116:119]
	v_mfma_f32_16x16x32_bf16 v[108:111], v[182:185], v[190:193], v[108:111]
	v_mfma_f32_16x16x32_bf16 v[100:103], v[172:175], v[198:201], v[100:103]
	v_mfma_f32_16x16x32_bf16 v[92:95], v[182:185], v[198:201], v[92:95]
	v_mfma_f32_16x16x32_bf16 v[84:87], v[172:175], v[206:209], v[84:87]
	v_mfma_f32_16x16x32_bf16 v[76:79], v[182:185], v[206:209], v[76:79]
	v_mfma_f32_16x16x32_bf16 v[68:71], v[172:175], v[214:217], v[68:71]
	v_mfma_f32_16x16x32_bf16 v[64:67], v[182:185], v[214:217], v[64:67]
	s_setprio 0
	s_barrier
; #define PG8_STAGE(bufoff, gbase, voff) do { _Pragma("unroll") for (int _i = 0; _i < 2; ++_i) \
;         __builtin_amdgcn_global_load_lds((const unsigned*)((const char*)(gbase) + (voff)[_i]), (LAS unsigned*)(lds + (bufoff) + ldsw + _i * 8192), 16, 0, 0); } while (0)
; #define PG8_LDA(dst, b, h) do { _Pragma("unroll") for (int m = 0; m < 4; ++m) _Pragma("unroll") for (int k = 0; k < 2; ++k) dst[m][k] = *(const LAS bf16x8*)(lds + PG8_SA(b, h) + aoff + m * 2048 + k * 1024); } while (0)
; #define PG8_MMA(ai, bj, At, Bt) do { __builtin_amdgcn_s_setprio(1); _Pragma("unroll") for (int m = 0; m < 4; ++m) _Pragma("unroll") for (int n = 0; n < 2; ++n) _Pragma("unroll") for (int k = 0; k < 2; ++k) \
;         acc[ai][bj][m][n] = __builtin_amdgcn_mfma_f32_16x16x32_bf16(Bt[n][k], At[m][k], acc[ai][bj][m][n], 0, 0, 0); __builtin_amdgcn_s_setprio(0); } while (0)
; #define PG8_WAIT_V(n) asm volatile("s_waitcnt vmcnt(" #n ")" ::: "memory")
; #define PG8_WAIT_L(n) asm volatile("s_waitcnt lgkmcnt(" #n ")" ::: "memory")
; #define PG8_BAR __builtin_amdgcn_s_barrier()
; #define PG8_SCHED __builtin_amdgcn_sched_barrier(0)
; template <class Epi, class Sched, bool ALIGN_EPI = true>
; __device__ __forceinline__ void gemm_phase(LAS unsigned char* lds, const Gemm g, const Sched& S, const Epi& E) {
;     ...
;             PG8_LDA(At, 1, 1); PG8_STAGE(PG8_SB(1, 0), b3, voffB); PG8_STAGE(PG8_SB(1, 1), b3 + hsB, voffB); PG8_STAGE(PG8_SA(1, 0), a3, voffA);
;             PG8_WAIT_V(8); PG8_WAIT_L(0); PG8_BAR; PG8_MMA(1, 0, At, B0); PG8_MMA(1, 1, At, B1); PG8_BAR; PG8_SCHED;
;         }
	s_add_i32 s40, s58, s33
	v_lshl_add_u64 v[218:219], v[218:219], 0, s[12:13]
	s_mov_b32 m0, s40
	s_nop 0
	global_load_lds_dwordx4 v[218:219], off
	s_add_i32 m0, s40, 0x2000
	s_add_u32 s38, s38, 0x80080
	v_lshl_add_u64 v[218:219], v[220:221], 0, s[12:13]
	s_addc_u32 s39, s39, 0
	s_add_i32 s40, s59, s33
	global_load_lds_dwordx4 v[218:219], off
	v_lshl_add_u64 v[218:219], s[38:39], 0, v[130:131]
	s_mov_b32 m0, s40
	s_nop 0
	global_load_lds_dwordx4 v[218:219], off
	v_lshl_add_u64 v[218:219], s[38:39], 0, v[134:135]
	s_add_i32 m0, s40, 0x2000
	s_nop 0
	global_load_lds_dwordx4 v[218:219], off
	v_lshl_add_u64 v[218:219], v[222:223], 0, s[12:13]
	s_mov_b32 m0, s48
	s_nop 0
	global_load_lds_dwordx4 v[218:219], off
	v_lshl_add_u64 v[218:219], v[224:225], 0, s[12:13]
	s_mov_b32 m0, s49
	s_nop 0
	global_load_lds_dwordx4 v[218:219], off
	ds_read_b128 v[186:189], v158 offset:49152
	ds_read_b128 v[190:193], v158 offset:50176
	ds_read_b128 v[194:197], v158 offset:51200
	ds_read_b128 v[198:201], v158 offset:52224
	ds_read_b128 v[202:205], v158 offset:53248
	ds_read_b128 v[206:209], v158 offset:54272
	ds_read_b128 v[210:213], v158 offset:55296
	ds_read_b128 v[214:217], v158 offset:56320
	s_waitcnt vmcnt(8)
	s_waitcnt lgkmcnt(0)
	s_barrier
	s_setprio 1
	s_waitcnt lgkmcnt(0)
	v_mfma_f32_16x16x32_bf16 v[60:63], v[144:147], v[186:189], v[60:63]
	v_mfma_f32_16x16x32_bf16 v[56:59], v[160:163], v[186:189], v[56:59]
	v_mfma_f32_16x16x32_bf16 v[48:51], v[144:147], v[194:197], v[48:51]
	v_mfma_f32_16x16x32_bf16 v[40:43], v[160:163], v[194:197], v[40:43]
	v_mfma_f32_16x16x32_bf16 v[32:35], v[144:147], v[202:205], v[32:35]
	v_mfma_f32_16x16x32_bf16 v[24:27], v[160:163], v[202:205], v[24:27]
	v_mfma_f32_16x16x32_bf16 v[16:19], v[144:147], v[210:213], v[16:19]
	v_mfma_f32_16x16x32_bf16 v[8:11], v[160:163], v[210:213], v[8:11]
	v_mfma_f32_16x16x32_bf16 v[60:63], v[148:151], v[190:193], v[60:63]
	v_mfma_f32_16x16x32_bf16 v[56:59], v[164:167], v[190:193], v[56:59]
	v_mfma_f32_16x16x32_bf16 v[48:51], v[148:151], v[198:201], v[48:51]
	v_mfma_f32_16x16x32_bf16 v[40:43], v[164:167], v[198:201], v[40:43]
	v_mfma_f32_16x16x32_bf16 v[32:35], v[148:151], v[206:209], v[32:35]
	v_mfma_f32_16x16x32_bf16 v[24:27], v[164:167], v[206:209], v[24:27]
	v_mfma_f32_16x16x32_bf16 v[16:19], v[148:151], v[214:217], v[16:19]
	v_mfma_f32_16x16x32_bf16 v[8:11], v[164:167], v[214:217], v[8:11]
	v_mfma_f32_16x16x32_bf16 v[52:55], v[168:171], v[186:189], v[52:55]
	v_mfma_f32_16x16x32_bf16 v[44:47], v[176:179], v[186:189], v[44:47]
	v_mfma_f32_16x16x32_bf16 v[36:39], v[168:171], v[194:197], v[36:39]
	v_mfma_f32_16x16x32_bf16 v[28:31], v[176:179], v[194:197], v[28:31]
	v_mfma_f32_16x16x32_bf16 v[20:23], v[168:171], v[202:205], v[20:23]
	v_mfma_f32_16x16x32_bf16 v[12:15], v[176:179], v[202:205], v[12:15]
	v_mfma_f32_16x16x32_bf16 v[4:7], v[168:171], v[210:213], v[4:7]
	v_mfma_f32_16x16x32_bf16 v[0:3], v[176:179], v[210:213], v[0:3]
	v_mfma_f32_16x16x32_bf16 v[52:55], v[172:175], v[190:193], v[52:55]
	v_mfma_f32_16x16x32_bf16 v[44:47], v[182:185], v[190:193], v[44:47]
	v_mfma_f32_16x16x32_bf16 v[36:39], v[172:175], v[198:201], v[36:39]
	v_mfma_f32_16x16x32_bf16 v[28:31], v[182:185], v[198:201], v[28:31]
	v_mfma_f32_16x16x32_bf16 v[20:23], v[172:175], v[206:209], v[20:23]
	v_mfma_f32_16x16x32_bf16 v[12:15], v[182:185], v[206:209], v[12:15]
	v_mfma_f32_16x16x32_bf16 v[4:7], v[172:175], v[214:217], v[4:7]
	v_mfma_f32_16x16x32_bf16 v[0:3], v[182:185], v[214:217], v[0:3]
	s_setprio 0
	s_barrier
	s_add_i32 s57, s57, 2
	s_add_u32 s36, s36, 0x100
	s_addc_u32 s37, s37, 0
	s_add_u32 s55, s55, 0x100
	s_addc_u32 s56, s56, 0
	s_cmp_gt_u32 s57, 29
	s_cbranch_scc0 .LBB0_704
	s_and_b64 vcc, exec, s[14:15]
	s_cbranch_vccz .LBB0_707
	s_barrier

; #define PG8_STAGE(bufoff, gbase, voff) do { _Pragma("unroll") for (int _i = 0; _i < 2; ++_i) \
;         __builtin_amdgcn_global_load_lds((const unsigned*)((const char*)(gbase) + (voff)[_i]), (LAS unsigned*)(lds + (bufoff) + ldsw + _i * 8192), 16, 0, 0); } while (0)
; #define PG8_LDA(dst, b, h) do { _Pragma("unroll") for (int m = 0; m < 4; ++m) _Pragma("unroll") for (int k = 0; k < 2; ++k) dst[m][k] = *(const LAS bf16x8*)(lds + PG8_SA(b, h) + aoff + m * 2048 + k * 1024); } while (0)
; #define PG8_LDB(dst, b, h) do { _Pragma("unroll") for (int n = 0; n < 2; ++n) _Pragma("unroll") for (int k = 0; k < 2; ++k) dst[n][k] = *(const LAS bf16x8*)(lds + PG8_SB(b, h) + boff + n * 2048 + k * 1024); } while (0)
; #define PG8_MMA(ai, bj, At, Bt) do { __builtin_amdgcn_s_setprio(1); _Pragma("unroll") for (int m = 0; m < 4; ++m) _Pragma("unroll") for (int n = 0; n < 2; ++n) _Pragma("unroll") for (int k = 0; k < 2; ++k) \
;         acc[ai][bj][m][n] = __builtin_amdgcn_mfma_f32_16x16x32_bf16(Bt[n][k], At[m][k], acc[ai][bj][m][n], 0, 0, 0); __builtin_amdgcn_s_setprio(0); } while (0)
; #define PG8_WAIT_V(n) asm volatile("s_waitcnt vmcnt(" #n ")" ::: "memory")
; #define PG8_WAIT_L(n) asm volatile("s_waitcnt lgkmcnt(" #n ")" ::: "memory")
; #define PG8_BAR __builtin_amdgcn_s_barrier()
; #define PG8_SCHED __builtin_amdgcn_sched_barrier(0)
; template <class Epi, class Sched, bool ALIGN_EPI = true>
; __device__ __forceinline__ void gemm_phase(LAS unsigned char* lds, const Gemm g, const Sched& S, const Epi& E) {
;     ...
;         for (int t = 0; t < nt; t += 2) {
;             const bool last = (t == nt - 2);
;             const char* a1 = cA + (size_t)(t + 1) * kstep;
;             const char* a2 = last ? nA : cA + (size_t)(t + 2) * kstep; const char* b2 = last ? nB : cB + (size_t)(t + 2) * kstep;
;             const char* a3 = a2 + kstep; const char* b3 = b2 + kstep;
;             PG8_LDB(B0, 0, 0); PG8_LDB(B1, 0, 1); PG8_SCHED; PG8_LDA(At, 0, 0); PG8_STAGE(PG8_SA(1, 1), a1 + hsA, voffA);
;             PG8_WAIT_V(8); PG8_WAIT_L(0); PG8_BAR; PG8_MMA(0, 0, At, B0); PG8_MMA(0, 1, At, B1); PG8_BAR; PG8_SCHED;
;             PG8_LDA(At, 0, 1); PG8_STAGE(PG8_SB(0, 0), b2, voffB); PG8_STAGE(PG8_SB(0, 1), b2 + hsB, voffB); PG8_STAGE(PG8_SA(0, 0), a2, voffA);
;             PG8_WAIT_V(8); PG8_WAIT_L(0); PG8_BAR; PG8_MMA(1, 0, At, B0); PG8_MMA(1, 1, At, B1); PG8_BAR; PG8_SCHED;
.LBB0_881:
	ds_read_b128 v[116:119], v184
	ds_read_b128 v[120:123], v184 offset:1024
	ds_read_b128 v[128:131], v184 offset:2048
	ds_read_b128 v[132:135], v184 offset:3072
	ds_read_b128 v[144:147], v185
	ds_read_b128 v[148:151], v185 offset:1024
	ds_read_b128 v[170:173], v185 offset:2048
	ds_read_b128 v[174:177], v185 offset:3072
	s_add_u32 s26, s6, 0xfffc0080
	s_addc_u32 s27, s7, -1
	s_cmp_eq_u32 s35, 12
	s_cselect_b32 s29, s23, s27
	s_cselect_b32 s28, s22, s26
	s_cselect_b32 s27, s9, s34
	s_cselect_b32 s26, s21, s31
	v_lshl_add_u64 v[178:179], s[6:7], 0, v[162:163]
	s_add_i32 m0, s42, 0xc000
	s_nop 0
	global_load_lds_dwordx4 v[178:179], off
	v_lshl_add_u64 v[178:179], s[6:7], 0, v[164:165]
	s_add_i32 m0, s42, 0xe000
	s_nop 0
	global_load_lds_dwordx4 v[178:179], off
	ds_read_b128 v[188:191], v186
	ds_read_b128 v[192:195], v186 offset:1024
	ds_read_b128 v[196:199], v186 offset:2048
	ds_read_b128 v[200:203], v186 offset:3072
	ds_read_b128 v[204:207], v186 offset:4096
	ds_read_b128 v[208:211], v186 offset:5120
	ds_read_b128 v[212:215], v186 offset:6144
	ds_read_b128 v[216:219], v186 offset:7168
	s_waitcnt vmcnt(8)
	s_waitcnt lgkmcnt(0)
	s_barrier
	s_setprio 1
	s_waitcnt lgkmcnt(0)
	v_mfma_f32_16x16x32_bf16 v[140:143], v[116:119], v[188:191], v[140:143]
	v_mfma_f32_16x16x32_bf16 v[64:67], v[128:131], v[188:191], v[64:67]
	v_mfma_f32_16x16x32_bf16 v[124:127], v[116:119], v[196:199], v[124:127]
	v_mfma_f32_16x16x32_bf16 v[52:55], v[128:131], v[196:199], v[52:55]
	v_mfma_f32_16x16x32_bf16 v[108:111], v[116:119], v[204:207], v[108:111]
	v_mfma_f32_16x16x32_bf16 v[44:47], v[128:131], v[204:207], v[44:47]
	v_mfma_f32_16x16x32_bf16 v[100:103], v[116:119], v[212:215], v[100:103]
	v_mfma_f32_16x16x32_bf16 v[36:39], v[128:131], v[212:215], v[36:39]
	v_mfma_f32_16x16x32_bf16 v[140:143], v[120:123], v[192:195], v[140:143]
	v_mfma_f32_16x16x32_bf16 v[64:67], v[132:135], v[192:195], v[64:67]
	v_mfma_f32_16x16x32_bf16 v[124:127], v[120:123], v[200:203], v[124:127]
	v_mfma_f32_16x16x32_bf16 v[52:55], v[132:135], v[200:203], v[52:55]
	v_mfma_f32_16x16x32_bf16 v[108:111], v[120:123], v[208:211], v[108:111]
	v_mfma_f32_16x16x32_bf16 v[44:47], v[132:135], v[208:211], v[44:47]
	v_mfma_f32_16x16x32_bf16 v[100:103], v[120:123], v[216:219], v[100:103]
	v_mfma_f32_16x16x32_bf16 v[36:39], v[132:135], v[216:219], v[36:39]
	v_mfma_f32_16x16x32_bf16 v[136:139], v[144:147], v[188:191], v[136:139]
	v_mfma_f32_16x16x32_bf16 v[56:59], v[170:173], v[188:191], v[56:59]
	v_mfma_f32_16x16x32_bf16 v[112:115], v[144:147], v[196:199], v[112:115]
	v_mfma_f32_16x16x32_bf16 v[48:51], v[170:173], v[196:199], v[48:51]
	v_mfma_f32_16x16x32_bf16 v[104:107], v[144:147], v[204:207], v[104:107]
	v_mfma_f32_16x16x32_bf16 v[40:43], v[170:173], v[204:207], v[40:43]
	v_mfma_f32_16x16x32_bf16 v[96:99], v[144:147], v[212:215], v[96:99]
	v_mfma_f32_16x16x32_bf16 v[32:35], v[170:173], v[212:215], v[32:35]
	v_mfma_f32_16x16x32_bf16 v[136:139], v[148:151], v[192:195], v[136:139]
	v_mfma_f32_16x16x32_bf16 v[56:59], v[174:177], v[192:195], v[56:59]
	v_mfma_f32_16x16x32_bf16 v[112:115], v[148:151], v[200:203], v[112:115]
	v_mfma_f32_16x16x32_bf16 v[48:51], v[174:177], v[200:203], v[48:51]
	v_mfma_f32_16x16x32_bf16 v[104:107], v[148:151], v[208:211], v[104:107]
	v_mfma_f32_16x16x32_bf16 v[40:43], v[174:177], v[208:211], v[40:43]
	v_mfma_f32_16x16x32_bf16 v[96:99], v[148:151], v[216:219], v[96:99]
	v_mfma_f32_16x16x32_bf16 v[32:35], v[174:177], v[216:219], v[32:35]
	s_setprio 0
	s_barrier
	s_add_i32 s36, s62, s33
	v_lshl_add_u64 v[178:179], s[26:27], 0, v[156:157]
	s_mov_b32 m0, s36
	s_nop 0
	global_load_lds_dwordx4 v[178:179], off
	s_add_i32 m0, s36, 0x2000
	s_add_u32 s36, s26, 0x40000
	v_lshl_add_u64 v[220:221], s[26:27], 0, v[160:161]
	s_addc_u32 s37, s27, 0
	s_add_i32 s38, s63, s33
	global_load_lds_dwordx4 v[220:221], off
	v_lshl_add_u64 v[222:223], s[36:37], 0, v[156:157]
	s_mov_b32 m0, s38
	v_lshl_add_u64 v[224:225], s[28:29], 0, v[158:159]
	global_load_lds_dwordx4 v[222:223], off
	v_lshl_add_u64 v[222:223], s[36:37], 0, v[160:161]
	s_add_i32 m0, s38, 0x2000
	s_nop 0
	global_load_lds_dwordx4 v[222:223], off
	v_lshl_add_u64 v[222:223], s[28:29], 0, v[154:155]
	s_mov_b32 m0, s42
	s_nop 0
	global_load_lds_dwordx4 v[222:223], off
	s_mov_b32 m0, s43
	s_nop 0
	global_load_lds_dwordx4 v[224:225], off
	ds_read_b128 v[188:191], v186 offset:16384
	ds_read_b128 v[192:195], v186 offset:17408
	ds_read_b128 v[196:199], v186 offset:18432
	ds_read_b128 v[200:203], v186 offset:19456
	ds_read_b128 v[204:207], v186 offset:20480
	ds_read_b128 v[208:211], v186 offset:21504
	ds_read_b128 v[212:215], v186 offset:22528
	ds_read_b128 v[216:219], v186 offset:23552
	s_waitcnt vmcnt(8)
	s_waitcnt lgkmcnt(0)
	s_barrier
; #define PG8_STAGE(bufoff, gbase, voff) do { _Pragma("unroll") for (int _i = 0; _i < 2; ++_i) \
;         __builtin_amdgcn_global_load_lds((const unsigned*)((const char*)(gbase) + (voff)[_i]), (LAS unsigned*)(lds + (bufoff) + ldsw + _i * 8192), 16, 0, 0); } while (0)
; #define PG8_LDA(dst, b, h) do { _Pragma("unroll") for (int m = 0; m < 4; ++m) _Pragma("unroll") for (int k = 0; k < 2; ++k) dst[m][k] = *(const LAS bf16x8*)(lds + PG8_SA(b, h) + aoff + m * 2048 + k * 1024); } while (0)
; #define PG8_LDB(dst, b, h) do { _Pragma("unroll") for (int n = 0; n < 2; ++n) _Pragma("unroll") for (int k = 0; k < 2; ++k) dst[n][k] = *(const LAS bf16x8*)(lds + PG8_SB(b, h) + boff + n * 2048 + k * 1024); } while (0)
; #define PG8_MMA(ai, bj, At, Bt) do { __builtin_amdgcn_s_setprio(1); _Pragma("unroll") for (int m = 0; m < 4; ++m) _Pragma("unroll") for (int n = 0; n < 2; ++n) _Pragma("unroll") for (int k = 0; k < 2; ++k) \
;         acc[ai][bj][m][n] = __builtin_amdgcn_mfma_f32_16x16x32_bf16(Bt[n][k], At[m][k], acc[ai][bj][m][n], 0, 0, 0); __builtin_amdgcn_s_setprio(0); } while (0)
; #define PG8_WAIT_V(n) asm volatile("s_waitcnt vmcnt(" #n ")" ::: "memory")
; #define PG8_WAIT_L(n) asm volatile("s_waitcnt lgkmcnt(" #n ")" ::: "memory")
; #define PG8_BAR __builtin_amdgcn_s_barrier()
; #define PG8_SCHED __builtin_amdgcn_sched_barrier(0)
; template <class Epi, class Sched, bool ALIGN_EPI = true>
; __device__ __forceinline__ void gemm_phase(LAS unsigned char* lds, const Gemm g, const Sched& S, const Epi& E) {
;     ...
;             PG8_WAIT_V(8); PG8_WAIT_L(0); PG8_BAR; PG8_MMA(1, 0, At, B0); PG8_MMA(1, 1, At, B1); PG8_BAR; PG8_SCHED;
;             PG8_LDB(B0, 1, 0); PG8_LDB(B1, 1, 1); PG8_SCHED; PG8_LDA(At, 1, 0); PG8_STAGE(PG8_SA(0, 1), a2 + hsA, voffA);
;             PG8_WAIT_V(8); PG8_WAIT_L(0); PG8_BAR; PG8_MMA(0, 0, At, B0); PG8_MMA(0, 1, At, B1); PG8_BAR; PG8_SCHED;
;             PG8_LDA(At, 1, 1); PG8_STAGE(PG8_SB(1, 0), b3, voffB); PG8_STAGE(PG8_SB(1, 1), b3 + hsB, voffB); PG8_STAGE(PG8_SA(1, 0), a3, voffA);
;             PG8_WAIT_V(8); PG8_WAIT_L(0); PG8_BAR; PG8_MMA(1, 0, At, B0); PG8_MMA(1, 1, At, B1); PG8_BAR; PG8_SCHED;
	s_setprio 1
	s_waitcnt lgkmcnt(0)
	v_mfma_f32_16x16x32_bf16 v[92:95], v[116:119], v[188:191], v[92:95]
	v_mfma_f32_16x16x32_bf16 v[28:31], v[128:131], v[188:191], v[28:31]
	v_mfma_f32_16x16x32_bf16 v[84:87], v[116:119], v[196:199], v[84:87]
	v_mfma_f32_16x16x32_bf16 v[20:23], v[128:131], v[196:199], v[20:23]
	v_mfma_f32_16x16x32_bf16 v[76:79], v[116:119], v[204:207], v[76:79]
	v_mfma_f32_16x16x32_bf16 v[12:15], v[128:131], v[204:207], v[12:15]
	v_mfma_f32_16x16x32_bf16 v[68:71], v[116:119], v[212:215], v[68:71]
	v_mfma_f32_16x16x32_bf16 v[4:7], v[128:131], v[212:215], v[4:7]
	v_mfma_f32_16x16x32_bf16 v[92:95], v[120:123], v[192:195], v[92:95]
	v_mfma_f32_16x16x32_bf16 v[28:31], v[132:135], v[192:195], v[28:31]
	v_mfma_f32_16x16x32_bf16 v[84:87], v[120:123], v[200:203], v[84:87]
	v_mfma_f32_16x16x32_bf16 v[20:23], v[132:135], v[200:203], v[20:23]
	v_mfma_f32_16x16x32_bf16 v[76:79], v[120:123], v[208:211], v[76:79]
	v_mfma_f32_16x16x32_bf16 v[12:15], v[132:135], v[208:211], v[12:15]
	v_mfma_f32_16x16x32_bf16 v[68:71], v[120:123], v[216:219], v[68:71]
	v_mfma_f32_16x16x32_bf16 v[4:7], v[132:135], v[216:219], v[4:7]
	v_mfma_f32_16x16x32_bf16 v[88:91], v[144:147], v[188:191], v[88:91]
	v_mfma_f32_16x16x32_bf16 v[24:27], v[170:173], v[188:191], v[24:27]
	v_mfma_f32_16x16x32_bf16 v[80:83], v[144:147], v[196:199], v[80:83]
	v_mfma_f32_16x16x32_bf16 v[16:19], v[170:173], v[196:199], v[16:19]
	v_mfma_f32_16x16x32_bf16 v[72:75], v[144:147], v[204:207], v[72:75]
	v_mfma_f32_16x16x32_bf16 v[8:11], v[170:173], v[204:207], v[8:11]
	v_mfma_f32_16x16x32_bf16 v[60:63], v[144:147], v[212:215], v[60:63]
	v_mfma_f32_16x16x32_bf16 v[0:3], v[170:173], v[212:215], v[0:3]
	v_mfma_f32_16x16x32_bf16 v[88:91], v[148:151], v[192:195], v[88:91]
	v_mfma_f32_16x16x32_bf16 v[24:27], v[174:177], v[192:195], v[24:27]
	v_mfma_f32_16x16x32_bf16 v[80:83], v[148:151], v[200:203], v[80:83]
	v_mfma_f32_16x16x32_bf16 v[16:19], v[174:177], v[200:203], v[16:19]
	v_mfma_f32_16x16x32_bf16 v[72:75], v[148:151], v[208:211], v[72:75]
	v_mfma_f32_16x16x32_bf16 v[8:11], v[174:177], v[208:211], v[8:11]
	v_mfma_f32_16x16x32_bf16 v[60:63], v[148:151], v[216:219], v[60:63]
	v_mfma_f32_16x16x32_bf16 v[0:3], v[174:177], v[216:219], v[0:3]
	s_setprio 0
	s_barrier
	s_add_i32 s36, 0, 0x18000
	s_add_i32 s37, 0, 0x1c000
	v_add_u32_e32 v132, s36, v182
	v_add_u32_e32 v174, s37, v182
	ds_read_b128 v[116:119], v132
	ds_read_b128 v[120:123], v132 offset:1024
	ds_read_b128 v[128:131], v132 offset:2048
	ds_read_b128 v[132:135], v132 offset:3072
	ds_read_b128 v[144:147], v174
	ds_read_b128 v[148:151], v174 offset:1024
	ds_read_b128 v[170:173], v174 offset:2048
	ds_read_b128 v[174:177], v174 offset:3072
	s_add_u32 s28, s28, 0x40000
	s_addc_u32 s29, s29, 0
	s_mov_b32 m0, s44
	v_lshl_add_u64 v[226:227], s[28:29], 0, v[154:155]
	global_load_lds_dwordx4 v[226:227], off
	v_lshl_add_u64 v[226:227], s[28:29], 0, v[158:159]
	s_mov_b32 m0, s45
	s_nop 0
	global_load_lds_dwordx4 v[226:227], off
	ds_read_b128 v[188:191], v186 offset:32768
	ds_read_b128 v[192:195], v186 offset:33792
	ds_read_b128 v[196:199], v186 offset:34816
	ds_read_b128 v[200:203], v186 offset:35840
	ds_read_b128 v[204:207], v186 offset:36864
	ds_read_b128 v[208:211], v186 offset:37888
	ds_read_b128 v[212:215], v186 offset:38912
	ds_read_b128 v[216:219], v186 offset:39936
	s_waitcnt vmcnt(8)
	s_waitcnt lgkmcnt(0)
	s_barrier
	s_setprio 1
	s_waitcnt lgkmcnt(0)
	v_mfma_f32_16x16x32_bf16 v[140:143], v[116:119], v[188:191], v[140:143]
	v_mfma_f32_16x16x32_bf16 v[64:67], v[128:131], v[188:191], v[64:67]
	v_mfma_f32_16x16x32_bf16 v[124:127], v[116:119], v[196:199], v[124:127]
	v_mfma_f32_16x16x32_bf16 v[52:55], v[128:131], v[196:199], v[52:55]
	v_mfma_f32_16x16x32_bf16 v[108:111], v[116:119], v[204:207], v[108:111]
	v_mfma_f32_16x16x32_bf16 v[44:47], v[128:131], v[204:207], v[44:47]
	v_mfma_f32_16x16x32_bf16 v[100:103], v[116:119], v[212:215], v[100:103]
	v_mfma_f32_16x16x32_bf16 v[36:39], v[128:131], v[212:215], v[36:39]
	v_mfma_f32_16x16x32_bf16 v[140:143], v[120:123], v[192:195], v[140:143]
	v_mfma_f32_16x16x32_bf16 v[64:67], v[132:135], v[192:195], v[64:67]
	v_mfma_f32_16x16x32_bf16 v[124:127], v[120:123], v[200:203], v[124:127]
	v_mfma_f32_16x16x32_bf16 v[52:55], v[132:135], v[200:203], v[52:55]
	v_mfma_f32_16x16x32_bf16 v[108:111], v[120:123], v[208:211], v[108:111]
	v_mfma_f32_16x16x32_bf16 v[44:47], v[132:135], v[208:211], v[44:47]
	v_mfma_f32_16x16x32_bf16 v[100:103], v[120:123], v[216:219], v[100:103]
	v_mfma_f32_16x16x32_bf16 v[36:39], v[132:135], v[216:219], v[36:39]
	v_mfma_f32_16x16x32_bf16 v[136:139], v[144:147], v[188:191], v[136:139]
	v_mfma_f32_16x16x32_bf16 v[56:59], v[170:173], v[188:191], v[56:59]
	v_mfma_f32_16x16x32_bf16 v[112:115], v[144:147], v[196:199], v[112:115]
	v_mfma_f32_16x16x32_bf16 v[48:51], v[170:173], v[196:199], v[48:51]
	v_mfma_f32_16x16x32_bf16 v[104:107], v[144:147], v[204:207], v[104:107]
	v_mfma_f32_16x16x32_bf16 v[40:43], v[170:173], v[204:207], v[40:43]
	v_mfma_f32_16x16x32_bf16 v[96:99], v[144:147], v[212:215], v[96:99]
	v_mfma_f32_16x16x32_bf16 v[32:35], v[170:173], v[212:215], v[32:35]
	v_mfma_f32_16x16x32_bf16 v[136:139], v[148:151], v[192:195], v[136:139]
	v_mfma_f32_16x16x32_bf16 v[56:59], v[174:177], v[192:195], v[56:59]
	v_mfma_f32_16x16x32_bf16 v[112:115], v[148:151], v[200:203], v[112:115]
	v_mfma_f32_16x16x32_bf16 v[48:51], v[174:177], v[200:203], v[48:51]
	v_mfma_f32_16x16x32_bf16 v[104:107], v[148:151], v[208:211], v[104:107]
	v_mfma_f32_16x16x32_bf16 v[40:43], v[174:177], v[208:211], v[40:43]
	v_mfma_f32_16x16x32_bf16 v[96:99], v[148:151], v[216:219], v[96:99]
	v_mfma_f32_16x16x32_bf16 v[32:35], v[174:177], v[216:219], v[32:35]
	s_setprio 0
	s_barrier
; #define PG8_STAGE(bufoff, gbase, voff) do { _Pragma("unroll") for (int _i = 0; _i < 2; ++_i) \
;         __builtin_amdgcn_global_load_lds((const unsigned*)((const char*)(gbase) + (voff)[_i]), (LAS unsigned*)(lds + (bufoff) + ldsw + _i * 8192), 16, 0, 0); } while (0)
; #define PG8_LDA(dst, b, h) do { _Pragma("unroll") for (int m = 0; m < 4; ++m) _Pragma("unroll") for (int k = 0; k < 2; ++k) dst[m][k] = *(const LAS bf16x8*)(lds + PG8_SA(b, h) + aoff + m * 2048 + k * 1024); } while (0)
; #define PG8_MMA(ai, bj, At, Bt) do { __builtin_amdgcn_s_setprio(1); _Pragma("unroll") for (int m = 0; m < 4; ++m) _Pragma("unroll") for (int n = 0; n < 2; ++n) _Pragma("unroll") for (int k = 0; k < 2; ++k) \
;         acc[ai][bj][m][n] = __builtin_amdgcn_mfma_f32_16x16x32_bf16(Bt[n][k], At[m][k], acc[ai][bj][m][n], 0, 0, 0); __builtin_amdgcn_s_setprio(0); } while (0)
; #define PG8_WAIT_V(n) asm volatile("s_waitcnt vmcnt(" #n ")" ::: "memory")
; #define PG8_WAIT_L(n) asm volatile("s_waitcnt lgkmcnt(" #n ")" ::: "memory")
; #define PG8_BAR __builtin_amdgcn_s_barrier()
; #define PG8_SCHED __builtin_amdgcn_sched_barrier(0)
; template <class Epi, class Sched, bool ALIGN_EPI = true>
; __device__ __forceinline__ void gemm_phase(LAS unsigned char* lds, const Gemm g, const Sched& S, const Epi& E) {
;     ...
;             PG8_LDA(At, 1, 1); PG8_STAGE(PG8_SB(1, 0), b3, voffB); PG8_STAGE(PG8_SB(1, 1), b3 + hsB, voffB); PG8_STAGE(PG8_SA(1, 0), a3, voffA);
;             PG8_WAIT_V(8); PG8_WAIT_L(0); PG8_BAR; PG8_MMA(1, 0, At, B0); PG8_MMA(1, 1, At, B1); PG8_BAR; PG8_SCHED;
;         }
	s_add_i32 s28, s36, s33
	v_lshl_add_u64 v[178:179], v[178:179], 0, s[94:95]
	s_mov_b32 m0, s28
	s_nop 0
	global_load_lds_dwordx4 v[178:179], off
	s_add_i32 m0, s28, 0x2000
	s_add_u32 s26, s26, 0x40080
	v_lshl_add_u64 v[178:179], v[220:221], 0, s[94:95]
	s_addc_u32 s27, s27, 0
	s_add_i32 s28, s37, s33
	global_load_lds_dwordx4 v[178:179], off
	v_lshl_add_u64 v[178:179], s[26:27], 0, v[156:157]
	s_mov_b32 m0, s28
	s_nop 0
	global_load_lds_dwordx4 v[178:179], off
	v_lshl_add_u64 v[178:179], s[26:27], 0, v[160:161]
	s_add_i32 m0, s28, 0x2000
	s_nop 0
	global_load_lds_dwordx4 v[178:179], off
	v_lshl_add_u64 v[178:179], v[222:223], 0, s[94:95]
	s_mov_b32 m0, s48
	s_nop 0
	global_load_lds_dwordx4 v[178:179], off
	v_lshl_add_u64 v[178:179], v[224:225], 0, s[94:95]
	s_mov_b32 m0, s49
	s_nop 0
	global_load_lds_dwordx4 v[178:179], off
	ds_read_b128 v[188:191], v186 offset:49152
	ds_read_b128 v[192:195], v186 offset:50176
	ds_read_b128 v[196:199], v186 offset:51200
	ds_read_b128 v[200:203], v186 offset:52224
	ds_read_b128 v[204:207], v186 offset:53248
	ds_read_b128 v[208:211], v186 offset:54272
	ds_read_b128 v[212:215], v186 offset:55296
	ds_read_b128 v[216:219], v186 offset:56320
	s_waitcnt vmcnt(8)
	s_waitcnt lgkmcnt(0)
	s_barrier
	s_setprio 1
	s_waitcnt lgkmcnt(0)
	v_mfma_f32_16x16x32_bf16 v[92:95], v[116:119], v[188:191], v[92:95]
	v_mfma_f32_16x16x32_bf16 v[28:31], v[128:131], v[188:191], v[28:31]
	v_mfma_f32_16x16x32_bf16 v[84:87], v[116:119], v[196:199], v[84:87]
	v_mfma_f32_16x16x32_bf16 v[20:23], v[128:131], v[196:199], v[20:23]
	v_mfma_f32_16x16x32_bf16 v[76:79], v[116:119], v[204:207], v[76:79]
	v_mfma_f32_16x16x32_bf16 v[12:15], v[128:131], v[204:207], v[12:15]
	v_mfma_f32_16x16x32_bf16 v[68:71], v[116:119], v[212:215], v[68:71]
	v_mfma_f32_16x16x32_bf16 v[4:7], v[128:131], v[212:215], v[4:7]
	v_mfma_f32_16x16x32_bf16 v[92:95], v[120:123], v[192:195], v[92:95]
	v_mfma_f32_16x16x32_bf16 v[28:31], v[132:135], v[192:195], v[28:31]
	v_mfma_f32_16x16x32_bf16 v[84:87], v[120:123], v[200:203], v[84:87]
	v_mfma_f32_16x16x32_bf16 v[20:23], v[132:135], v[200:203], v[20:23]
	v_mfma_f32_16x16x32_bf16 v[76:79], v[120:123], v[208:211], v[76:79]
	v_mfma_f32_16x16x32_bf16 v[12:15], v[132:135], v[208:211], v[12:15]
	v_mfma_f32_16x16x32_bf16 v[68:71], v[120:123], v[216:219], v[68:71]
	v_mfma_f32_16x16x32_bf16 v[4:7], v[132:135], v[216:219], v[4:7]
	v_mfma_f32_16x16x32_bf16 v[88:91], v[144:147], v[188:191], v[88:91]
	v_mfma_f32_16x16x32_bf16 v[24:27], v[170:173], v[188:191], v[24:27]
	v_mfma_f32_16x16x32_bf16 v[80:83], v[144:147], v[196:199], v[80:83]
	v_mfma_f32_16x16x32_bf16 v[16:19], v[170:173], v[196:199], v[16:19]
	v_mfma_f32_16x16x32_bf16 v[72:75], v[144:147], v[204:207], v[72:75]
	v_mfma_f32_16x16x32_bf16 v[8:11], v[170:173], v[204:207], v[8:11]
	v_mfma_f32_16x16x32_bf16 v[60:63], v[144:147], v[212:215], v[60:63]
	v_mfma_f32_16x16x32_bf16 v[0:3], v[170:173], v[212:215], v[0:3]
	v_mfma_f32_16x16x32_bf16 v[88:91], v[148:151], v[192:195], v[88:91]
	v_mfma_f32_16x16x32_bf16 v[24:27], v[174:177], v[192:195], v[24:27]
	v_mfma_f32_16x16x32_bf16 v[80:83], v[148:151], v[200:203], v[80:83]
	v_mfma_f32_16x16x32_bf16 v[16:19], v[174:177], v[200:203], v[16:19]
	v_mfma_f32_16x16x32_bf16 v[72:75], v[148:151], v[208:211], v[72:75]
	v_mfma_f32_16x16x32_bf16 v[8:11], v[174:177], v[208:211], v[8:11]
	v_mfma_f32_16x16x32_bf16 v[60:63], v[148:151], v[216:219], v[60:63]
	v_mfma_f32_16x16x32_bf16 v[0:3], v[174:177], v[216:219], v[0:3]
	s_setprio 0
	s_barrier
	s_add_i32 s35, s35, 2
	s_add_u32 s6, s6, 0x100
	s_addc_u32 s7, s7, 0
	s_add_u32 s31, s31, 0x100
	s_addc_u32 s34, s34, 0
	s_cmp_gt_u32 s35, 13
	s_cbranch_scc0 .LBB0_881
	s_and_b64 vcc, exec, s[96:97]
	s_cbranch_vccz .LBB0_884
	s_barrier

; #define PG8_STAGE(bufoff, gbase, voff) do { _Pragma("unroll") for (int _i = 0; _i < 2; ++_i) \
;         __builtin_amdgcn_global_load_lds((const unsigned*)((const char*)(gbase) + (voff)[_i]), (LAS unsigned*)(lds + (bufoff) + ldsw + _i * 8192), 16, 0, 0); } while (0)
; #define PG8_LDA(dst, b, h) do { _Pragma("unroll") for (int m = 0; m < 4; ++m) _Pragma("unroll") for (int k = 0; k < 2; ++k) dst[m][k] = *(const LAS bf16x8*)(lds + PG8_SA(b, h) + aoff + m * 2048 + k * 1024); } while (0)
; #define PG8_LDB(dst, b, h) do { _Pragma("unroll") for (int n = 0; n < 2; ++n) _Pragma("unroll") for (int k = 0; k < 2; ++k) dst[n][k] = *(const LAS bf16x8*)(lds + PG8_SB(b, h) + boff + n * 2048 + k * 1024); } while (0)
; #define PG8_MMA(ai, bj, At, Bt) do { __builtin_amdgcn_s_setprio(1); _Pragma("unroll") for (int m = 0; m < 4; ++m) _Pragma("unroll") for (int n = 0; n < 2; ++n) _Pragma("unroll") for (int k = 0; k < 2; ++k) \
;         acc[ai][bj][m][n] = __builtin_amdgcn_mfma_f32_16x16x32_bf16(Bt[n][k], At[m][k], acc[ai][bj][m][n], 0, 0, 0); __builtin_amdgcn_s_setprio(0); } while (0)
; template <class Epi, class Sched, bool ALIGN_EPI = true>
; __device__ __forceinline__ void gemm_phase(LAS unsigned char* lds, const Gemm g, const Sched& S, const Epi& E) {
;     ...
;         const bool has_next = S.next(ui + 1, nxt);
;         const char* nA = has_next ? (const char*)g.A + ((long)nxt.pm * g.mstride + g.moff) * (long)(g.lda * 2) : cA; const char* nB = has_next ? (const char*)g.Bt + (size_t)nxt.pn * tsB : cB;
;         for (int t = 0; t < nt; t += 2) {
;             const bool last = (t == nt - 2);
;             const char* a1 = cA + (size_t)(t + 1) * kstep;
;             const char* a2 = last ? nA : cA + (size_t)(t + 2) * kstep; const char* b2 = last ? nB : cB + (size_t)(t + 2) * kstep;
;             const char* a3 = a2 + kstep; const char* b3 = b2 + kstep;
;             PG8_LDB(B0, 0, 0); PG8_LDB(B1, 0, 1); PG8_SCHED; PG8_LDA(At, 0, 0); PG8_STAGE(PG8_SA(1, 1), a1 + hsA, voffA);
;             PG8_WAIT_V(8); PG8_WAIT_L(0); PG8_BAR; PG8_MMA(0, 0, At, B0); PG8_MMA(0, 1, At, B1); PG8_BAR; PG8_SCHED;
;             PG8_LDA(At, 0, 1); PG8_STAGE(PG8_SB(0, 0), b2, voffB); PG8_STAGE(PG8_SB(0, 1), b2 + hsB, voffB); PG8_STAGE(PG8_SA(0, 0), a2, voffA);
;             PG8_WAIT_V(8); PG8_WAIT_L(0); PG8_BAR; PG8_MMA(1, 0, At, B0); PG8_MMA(1, 1, At, B1); PG8_BAR; PG8_SCHED;
.LBB0_999:
	ds_read_b128 v[144:147], v156
	ds_read_b128 v[148:151], v156 offset:1024
	ds_read_b128 v[160:163], v156 offset:2048
	ds_read_b128 v[164:167], v156 offset:3072
	ds_read_b128 v[168:171], v157
	ds_read_b128 v[172:175], v157 offset:1024
	ds_read_b128 v[176:179], v157 offset:2048
	ds_read_b128 v[182:185], v157 offset:3072
	s_add_u32 s4, s26, 0x100
	s_addc_u32 s5, s27, 0
	s_cmp_eq_u32 s53, 40
	s_cselect_b32 s31, s23, s5
	s_cselect_b32 s30, s22, s4
	s_cselect_b32 s29, s25, s52
	s_cselect_b32 s28, s24, s51
	v_lshl_add_u64 v[218:219], s[26:27], 0, v[136:137]
	s_add_i32 m0, s34, 0xc000
	s_nop 0
	global_load_lds_dwordx4 v[218:219], off
	v_lshl_add_u64 v[218:219], s[26:27], 0, v[138:139]
	s_add_i32 m0, s34, 0xe000
	s_nop 0
	global_load_lds_dwordx4 v[218:219], off
	ds_read_b128 v[186:189], v158
	ds_read_b128 v[190:193], v158 offset:1024
	ds_read_b128 v[194:197], v158 offset:2048
	ds_read_b128 v[198:201], v158 offset:3072
	ds_read_b128 v[202:205], v158 offset:4096
	ds_read_b128 v[206:209], v158 offset:5120
	ds_read_b128 v[210:213], v158 offset:6144
	ds_read_b128 v[214:217], v158 offset:7168
	s_waitcnt vmcnt(8)
	s_waitcnt lgkmcnt(0)
	s_barrier
	s_setprio 1
	s_waitcnt lgkmcnt(0)
	v_mfma_f32_16x16x32_bf16 v[124:127], v[144:147], v[186:189], v[124:127]
	v_mfma_f32_16x16x32_bf16 v[120:123], v[160:163], v[186:189], v[120:123]
	v_mfma_f32_16x16x32_bf16 v[112:115], v[144:147], v[194:197], v[112:115]
	v_mfma_f32_16x16x32_bf16 v[104:107], v[160:163], v[194:197], v[104:107]
	v_mfma_f32_16x16x32_bf16 v[96:99], v[144:147], v[202:205], v[96:99]
	v_mfma_f32_16x16x32_bf16 v[88:91], v[160:163], v[202:205], v[88:91]
	v_mfma_f32_16x16x32_bf16 v[80:83], v[144:147], v[210:213], v[80:83]
	v_mfma_f32_16x16x32_bf16 v[72:75], v[160:163], v[210:213], v[72:75]
	v_mfma_f32_16x16x32_bf16 v[124:127], v[148:151], v[190:193], v[124:127]
	v_mfma_f32_16x16x32_bf16 v[120:123], v[164:167], v[190:193], v[120:123]
	v_mfma_f32_16x16x32_bf16 v[112:115], v[148:151], v[198:201], v[112:115]
	v_mfma_f32_16x16x32_bf16 v[104:107], v[164:167], v[198:201], v[104:107]
	v_mfma_f32_16x16x32_bf16 v[96:99], v[148:151], v[206:209], v[96:99]
	v_mfma_f32_16x16x32_bf16 v[88:91], v[164:167], v[206:209], v[88:91]
	v_mfma_f32_16x16x32_bf16 v[80:83], v[148:151], v[214:217], v[80:83]
	v_mfma_f32_16x16x32_bf16 v[72:75], v[164:167], v[214:217], v[72:75]
	v_mfma_f32_16x16x32_bf16 v[116:119], v[168:171], v[186:189], v[116:119]
	v_mfma_f32_16x16x32_bf16 v[108:111], v[176:179], v[186:189], v[108:111]
	v_mfma_f32_16x16x32_bf16 v[100:103], v[168:171], v[194:197], v[100:103]
	v_mfma_f32_16x16x32_bf16 v[92:95], v[176:179], v[194:197], v[92:95]
	v_mfma_f32_16x16x32_bf16 v[84:87], v[168:171], v[202:205], v[84:87]
	v_mfma_f32_16x16x32_bf16 v[76:79], v[176:179], v[202:205], v[76:79]
	v_mfma_f32_16x16x32_bf16 v[68:71], v[168:171], v[210:213], v[68:71]
	v_mfma_f32_16x16x32_bf16 v[64:67], v[176:179], v[210:213], v[64:67]
	v_mfma_f32_16x16x32_bf16 v[116:119], v[172:175], v[190:193], v[116:119]
	v_mfma_f32_16x16x32_bf16 v[108:111], v[182:185], v[190:193], v[108:111]
	v_mfma_f32_16x16x32_bf16 v[100:103], v[172:175], v[198:201], v[100:103]
	v_mfma_f32_16x16x32_bf16 v[92:95], v[182:185], v[198:201], v[92:95]
	v_mfma_f32_16x16x32_bf16 v[84:87], v[172:175], v[206:209], v[84:87]
	v_mfma_f32_16x16x32_bf16 v[76:79], v[182:185], v[206:209], v[76:79]
	v_mfma_f32_16x16x32_bf16 v[68:71], v[172:175], v[214:217], v[68:71]
	v_mfma_f32_16x16x32_bf16 v[64:67], v[182:185], v[214:217], v[64:67]
	s_setprio 0
	s_barrier
	s_add_i32 s26, s45, s33
	v_lshl_add_u64 v[218:219], s[28:29], 0, v[130:131]
	s_mov_b32 m0, s26
	s_nop 0
	global_load_lds_dwordx4 v[218:219], off
	s_add_i32 m0, s26, 0x2000
	s_add_u32 s26, s28, 0xb0000
	v_lshl_add_u64 v[220:221], s[28:29], 0, v[134:135]
	s_addc_u32 s27, s29, 0
	s_add_i32 s54, s46, s33
	global_load_lds_dwordx4 v[220:221], off
	v_lshl_add_u64 v[222:223], s[26:27], 0, v[130:131]
	s_mov_b32 m0, s54
	v_lshl_add_u64 v[224:225], s[30:31], 0, v[132:133]
	global_load_lds_dwordx4 v[222:223], off
	v_lshl_add_u64 v[222:223], s[26:27], 0, v[134:135]
	s_add_i32 m0, s54, 0x2000
	s_nop 0
	global_load_lds_dwordx4 v[222:223], off
	v_lshl_add_u64 v[222:223], s[30:31], 0, v[128:129]
	s_mov_b32 m0, s34
	s_nop 0
	global_load_lds_dwordx4 v[222:223], off
	s_mov_b32 m0, s35
	s_nop 0
	global_load_lds_dwordx4 v[224:225], off
	ds_read_b128 v[186:189], v158 offset:16384
	ds_read_b128 v[190:193], v158 offset:17408
	ds_read_b128 v[194:197], v158 offset:18432
	ds_read_b128 v[198:201], v158 offset:19456
	ds_read_b128 v[202:205], v158 offset:20480
	ds_read_b128 v[206:209], v158 offset:21504
	ds_read_b128 v[210:213], v158 offset:22528
	ds_read_b128 v[214:217], v158 offset:23552
	s_waitcnt vmcnt(8)
	s_waitcnt lgkmcnt(0)
	s_barrier
; #define PG8_STAGE(bufoff, gbase, voff) do { _Pragma("unroll") for (int _i = 0; _i < 2; ++_i) \
;         __builtin_amdgcn_global_load_lds((const unsigned*)((const char*)(gbase) + (voff)[_i]), (LAS unsigned*)(lds + (bufoff) + ldsw + _i * 8192), 16, 0, 0); } while (0)
; #define PG8_LDA(dst, b, h) do { _Pragma("unroll") for (int m = 0; m < 4; ++m) _Pragma("unroll") for (int k = 0; k < 2; ++k) dst[m][k] = *(const LAS bf16x8*)(lds + PG8_SA(b, h) + aoff + m * 2048 + k * 1024); } while (0)
; #define PG8_LDB(dst, b, h) do { _Pragma("unroll") for (int n = 0; n < 2; ++n) _Pragma("unroll") for (int k = 0; k < 2; ++k) dst[n][k] = *(const LAS bf16x8*)(lds + PG8_SB(b, h) + boff + n * 2048 + k * 1024); } while (0)
; #define PG8_MMA(ai, bj, At, Bt) do { __builtin_amdgcn_s_setprio(1); _Pragma("unroll") for (int m = 0; m < 4; ++m) _Pragma("unroll") for (int n = 0; n < 2; ++n) _Pragma("unroll") for (int k = 0; k < 2; ++k) \
;         acc[ai][bj][m][n] = __builtin_amdgcn_mfma_f32_16x16x32_bf16(Bt[n][k], At[m][k], acc[ai][bj][m][n], 0, 0, 0); __builtin_amdgcn_s_setprio(0); } while (0)
; #define PG8_WAIT_V(n) asm volatile("s_waitcnt vmcnt(" #n ")" ::: "memory")
; #define PG8_WAIT_L(n) asm volatile("s_waitcnt lgkmcnt(" #n ")" ::: "memory")
; #define PG8_BAR __builtin_amdgcn_s_barrier()
; #define PG8_SCHED __builtin_amdgcn_sched_barrier(0)
; template <class Epi, class Sched, bool ALIGN_EPI = true>
; __device__ __forceinline__ void gemm_phase(LAS unsigned char* lds, const Gemm g, const Sched& S, const Epi& E) {
;     ...
;             PG8_WAIT_V(8); PG8_WAIT_L(0); PG8_BAR; PG8_MMA(1, 0, At, B0); PG8_MMA(1, 1, At, B1); PG8_BAR; PG8_SCHED;
;             PG8_LDB(B0, 1, 0); PG8_LDB(B1, 1, 1); PG8_SCHED; PG8_LDA(At, 1, 0); PG8_STAGE(PG8_SA(0, 1), a2 + hsA, voffA);
;             PG8_WAIT_V(8); PG8_WAIT_L(0); PG8_BAR; PG8_MMA(0, 0, At, B0); PG8_MMA(0, 1, At, B1); PG8_BAR; PG8_SCHED;
	s_setprio 1
	s_waitcnt lgkmcnt(0)
	v_mfma_f32_16x16x32_bf16 v[60:63], v[144:147], v[186:189], v[60:63]
	v_mfma_f32_16x16x32_bf16 v[56:59], v[160:163], v[186:189], v[56:59]
	v_mfma_f32_16x16x32_bf16 v[48:51], v[144:147], v[194:197], v[48:51]
	v_mfma_f32_16x16x32_bf16 v[40:43], v[160:163], v[194:197], v[40:43]
	v_mfma_f32_16x16x32_bf16 v[32:35], v[144:147], v[202:205], v[32:35]
	v_mfma_f32_16x16x32_bf16 v[24:27], v[160:163], v[202:205], v[24:27]
	v_mfma_f32_16x16x32_bf16 v[16:19], v[144:147], v[210:213], v[16:19]
	v_mfma_f32_16x16x32_bf16 v[8:11], v[160:163], v[210:213], v[8:11]
	v_mfma_f32_16x16x32_bf16 v[60:63], v[148:151], v[190:193], v[60:63]
	v_mfma_f32_16x16x32_bf16 v[56:59], v[164:167], v[190:193], v[56:59]
	v_mfma_f32_16x16x32_bf16 v[48:51], v[148:151], v[198:201], v[48:51]
	v_mfma_f32_16x16x32_bf16 v[40:43], v[164:167], v[198:201], v[40:43]
	v_mfma_f32_16x16x32_bf16 v[32:35], v[148:151], v[206:209], v[32:35]
	v_mfma_f32_16x16x32_bf16 v[24:27], v[164:167], v[206:209], v[24:27]
	v_mfma_f32_16x16x32_bf16 v[16:19], v[148:151], v[214:217], v[16:19]
	v_mfma_f32_16x16x32_bf16 v[8:11], v[164:167], v[214:217], v[8:11]
	v_mfma_f32_16x16x32_bf16 v[52:55], v[168:171], v[186:189], v[52:55]
	v_mfma_f32_16x16x32_bf16 v[44:47], v[176:179], v[186:189], v[44:47]
	v_mfma_f32_16x16x32_bf16 v[36:39], v[168:171], v[194:197], v[36:39]
	v_mfma_f32_16x16x32_bf16 v[28:31], v[176:179], v[194:197], v[28:31]
	v_mfma_f32_16x16x32_bf16 v[20:23], v[168:171], v[202:205], v[20:23]
	v_mfma_f32_16x16x32_bf16 v[12:15], v[176:179], v[202:205], v[12:15]
	v_mfma_f32_16x16x32_bf16 v[4:7], v[168:171], v[210:213], v[4:7]
	v_mfma_f32_16x16x32_bf16 v[0:3], v[176:179], v[210:213], v[0:3]
	v_mfma_f32_16x16x32_bf16 v[52:55], v[172:175], v[190:193], v[52:55]
	v_mfma_f32_16x16x32_bf16 v[44:47], v[182:185], v[190:193], v[44:47]
	v_mfma_f32_16x16x32_bf16 v[36:39], v[172:175], v[198:201], v[36:39]
	v_mfma_f32_16x16x32_bf16 v[28:31], v[182:185], v[198:201], v[28:31]
	v_mfma_f32_16x16x32_bf16 v[20:23], v[172:175], v[206:209], v[20:23]
	v_mfma_f32_16x16x32_bf16 v[12:15], v[182:185], v[206:209], v[12:15]
	v_mfma_f32_16x16x32_bf16 v[4:7], v[172:175], v[214:217], v[4:7]
	v_mfma_f32_16x16x32_bf16 v[0:3], v[182:185], v[214:217], v[0:3]
	s_setprio 0
	s_barrier
	s_add_i32 s54, 0, 0x18000
	v_add_u32_e32 v159, s54, v154
	s_add_i32 s55, 0, 0x1c000
	ds_read_b128 v[144:147], v159
	ds_read_b128 v[148:151], v159 offset:1024
	ds_read_b128 v[160:163], v159 offset:2048
	ds_read_b128 v[164:167], v159 offset:3072
	v_add_u32_e32 v159, s55, v154
	ds_read_b128 v[168:171], v159
	ds_read_b128 v[172:175], v159 offset:1024
	ds_read_b128 v[176:179], v159 offset:2048
	ds_read_b128 v[182:185], v159 offset:3072
	s_add_u32 s26, s30, 0xb0000
	s_addc_u32 s27, s31, 0
	s_mov_b32 m0, s36
	v_lshl_add_u64 v[226:227], s[26:27], 0, v[128:129]
	global_load_lds_dwordx4 v[226:227], off
	v_lshl_add_u64 v[226:227], s[26:27], 0, v[132:133]
	s_mov_b32 m0, s37
	s_nop 0
	global_load_lds_dwordx4 v[226:227], off
	ds_read_b128 v[186:189], v158 offset:32768
	ds_read_b128 v[190:193], v158 offset:33792
	ds_read_b128 v[194:197], v158 offset:34816
	ds_read_b128 v[198:201], v158 offset:35840
	ds_read_b128 v[202:205], v158 offset:36864
	ds_read_b128 v[206:209], v158 offset:37888
	ds_read_b128 v[210:213], v158 offset:38912
	ds_read_b128 v[214:217], v158 offset:39936
	s_waitcnt vmcnt(8)
	s_waitcnt lgkmcnt(0)
	s_barrier
	s_setprio 1
	s_waitcnt lgkmcnt(0)
	v_mfma_f32_16x16x32_bf16 v[124:127], v[144:147], v[186:189], v[124:127]
	v_mfma_f32_16x16x32_bf16 v[120:123], v[160:163], v[186:189], v[120:123]
	v_mfma_f32_16x16x32_bf16 v[112:115], v[144:147], v[194:197], v[112:115]
	v_mfma_f32_16x16x32_bf16 v[104:107], v[160:163], v[194:197], v[104:107]
	v_mfma_f32_16x16x32_bf16 v[96:99], v[144:147], v[202:205], v[96:99]
	v_mfma_f32_16x16x32_bf16 v[88:91], v[160:163], v[202:205], v[88:91]
	v_mfma_f32_16x16x32_bf16 v[80:83], v[144:147], v[210:213], v[80:83]
	v_mfma_f32_16x16x32_bf16 v[72:75], v[160:163], v[210:213], v[72:75]
	v_mfma_f32_16x16x32_bf16 v[124:127], v[148:151], v[190:193], v[124:127]
	v_mfma_f32_16x16x32_bf16 v[120:123], v[164:167], v[190:193], v[120:123]
	v_mfma_f32_16x16x32_bf16 v[112:115], v[148:151], v[198:201], v[112:115]
	v_mfma_f32_16x16x32_bf16 v[104:107], v[164:167], v[198:201], v[104:107]
	v_mfma_f32_16x16x32_bf16 v[96:99], v[148:151], v[206:209], v[96:99]
	v_mfma_f32_16x16x32_bf16 v[88:91], v[164:167], v[206:209], v[88:91]
	v_mfma_f32_16x16x32_bf16 v[80:83], v[148:151], v[214:217], v[80:83]
	v_mfma_f32_16x16x32_bf16 v[72:75], v[164:167], v[214:217], v[72:75]
	v_mfma_f32_16x16x32_bf16 v[116:119], v[168:171], v[186:189], v[116:119]
	v_mfma_f32_16x16x32_bf16 v[108:111], v[176:179], v[186:189], v[108:111]
	v_mfma_f32_16x16x32_bf16 v[100:103], v[168:171], v[194:197], v[100:103]
	v_mfma_f32_16x16x32_bf16 v[92:95], v[176:179], v[194:197], v[92:95]
	v_mfma_f32_16x16x32_bf16 v[84:87], v[168:171], v[202:205], v[84:87]
	v_mfma_f32_16x16x32_bf16 v[76:79], v[176:179], v[202:205], v[76:79]
	v_mfma_f32_16x16x32_bf16 v[68:71], v[168:171], v[210:213], v[68:71]
	v_mfma_f32_16x16x32_bf16 v[64:67], v[176:179], v[210:213], v[64:67]
	v_mfma_f32_16x16x32_bf16 v[116:119], v[172:175], v[190:193], v[116:119]
	v_mfma_f32_16x16x32_bf16 v[108:111], v[182:185], v[190:193], v[108:111]
	v_mfma_f32_16x16x32_bf16 v[100:103], v[172:175], v[198:201], v[100:103]
	v_mfma_f32_16x16x32_bf16 v[92:95], v[182:185], v[198:201], v[92:95]
	v_mfma_f32_16x16x32_bf16 v[84:87], v[172:175], v[206:209], v[84:87]
	v_mfma_f32_16x16x32_bf16 v[76:79], v[182:185], v[206:209], v[76:79]
	v_mfma_f32_16x16x32_bf16 v[68:71], v[172:175], v[214:217], v[68:71]
	v_mfma_f32_16x16x32_bf16 v[64:67], v[182:185], v[214:217], v[64:67]
	s_setprio 0
	s_barrier
; #define PG8_STAGE(bufoff, gbase, voff) do { _Pragma("unroll") for (int _i = 0; _i < 2; ++_i) \
;         __builtin_amdgcn_global_load_lds((const unsigned*)((const char*)(gbase) + (voff)[_i]), (LAS unsigned*)(lds + (bufoff) + ldsw + _i * 8192), 16, 0, 0); } while (0)
; #define PG8_LDA(dst, b, h) do { _Pragma("unroll") for (int m = 0; m < 4; ++m) _Pragma("unroll") for (int k = 0; k < 2; ++k) dst[m][k] = *(const LAS bf16x8*)(lds + PG8_SA(b, h) + aoff + m * 2048 + k * 1024); } while (0)
; #define PG8_MMA(ai, bj, At, Bt) do { __builtin_amdgcn_s_setprio(1); _Pragma("unroll") for (int m = 0; m < 4; ++m) _Pragma("unroll") for (int n = 0; n < 2; ++n) _Pragma("unroll") for (int k = 0; k < 2; ++k) \
;         acc[ai][bj][m][n] = __builtin_amdgcn_mfma_f32_16x16x32_bf16(Bt[n][k], At[m][k], acc[ai][bj][m][n], 0, 0, 0); __builtin_amdgcn_s_setprio(0); } while (0)
; #define PG8_WAIT_V(n) asm volatile("s_waitcnt vmcnt(" #n ")" ::: "memory")
; #define PG8_WAIT_L(n) asm volatile("s_waitcnt lgkmcnt(" #n ")" ::: "memory")
; #define PG8_BAR __builtin_amdgcn_s_barrier()
; #define PG8_SCHED __builtin_amdgcn_sched_barrier(0)
; template <class Epi, class Sched, bool ALIGN_EPI = true>
; __device__ __forceinline__ void gemm_phase(LAS unsigned char* lds, const Gemm g, const Sched& S, const Epi& E) {
;     ...
;             PG8_LDA(At, 1, 1); PG8_STAGE(PG8_SB(1, 0), b3, voffB); PG8_STAGE(PG8_SB(1, 1), b3 + hsB, voffB); PG8_STAGE(PG8_SA(1, 0), a3, voffA);
;             PG8_WAIT_V(8); PG8_WAIT_L(0); PG8_BAR; PG8_MMA(1, 0, At, B0); PG8_MMA(1, 1, At, B1); PG8_BAR; PG8_SCHED;
;         }
;         if constexpr (ALIGN_EPI) { if (wr == 0) PG8_BAR; }
	s_add_i32 s26, s54, s33
	v_lshl_add_u64 v[218:219], v[218:219], 0, s[8:9]
	s_mov_b32 m0, s26
	s_nop 0
	global_load_lds_dwordx4 v[218:219], off
	s_add_i32 m0, s26, 0x2000
	s_add_u32 s26, s28, 0xb0080
	v_lshl_add_u64 v[218:219], v[220:221], 0, s[8:9]
	s_addc_u32 s27, s29, 0
	s_add_i32 s28, s55, s33
	global_load_lds_dwordx4 v[218:219], off
	v_lshl_add_u64 v[218:219], s[26:27], 0, v[130:131]
	s_mov_b32 m0, s28
	s_nop 0
	global_load_lds_dwordx4 v[218:219], off
	v_lshl_add_u64 v[218:219], s[26:27], 0, v[134:135]
	s_add_i32 m0, s28, 0x2000
	s_nop 0
	global_load_lds_dwordx4 v[218:219], off
	v_lshl_add_u64 v[218:219], v[222:223], 0, s[8:9]
	s_mov_b32 m0, s40
	s_nop 0
	global_load_lds_dwordx4 v[218:219], off
	v_lshl_add_u64 v[218:219], v[224:225], 0, s[8:9]
	s_mov_b32 m0, s41
	s_nop 0
	global_load_lds_dwordx4 v[218:219], off
	ds_read_b128 v[186:189], v158 offset:49152
	ds_read_b128 v[190:193], v158 offset:50176
	ds_read_b128 v[194:197], v158 offset:51200
	ds_read_b128 v[198:201], v158 offset:52224
	ds_read_b128 v[202:205], v158 offset:53248
	ds_read_b128 v[206:209], v158 offset:54272
	ds_read_b128 v[210:213], v158 offset:55296
	ds_read_b128 v[214:217], v158 offset:56320
	s_waitcnt vmcnt(8)
	s_waitcnt lgkmcnt(0)
	s_barrier
	s_setprio 1
	s_waitcnt lgkmcnt(0)
	v_mfma_f32_16x16x32_bf16 v[60:63], v[144:147], v[186:189], v[60:63]
	v_mfma_f32_16x16x32_bf16 v[56:59], v[160:163], v[186:189], v[56:59]
	v_mfma_f32_16x16x32_bf16 v[48:51], v[144:147], v[194:197], v[48:51]
	v_mfma_f32_16x16x32_bf16 v[40:43], v[160:163], v[194:197], v[40:43]
	v_mfma_f32_16x16x32_bf16 v[32:35], v[144:147], v[202:205], v[32:35]
	v_mfma_f32_16x16x32_bf16 v[24:27], v[160:163], v[202:205], v[24:27]
	v_mfma_f32_16x16x32_bf16 v[16:19], v[144:147], v[210:213], v[16:19]
	v_mfma_f32_16x16x32_bf16 v[8:11], v[160:163], v[210:213], v[8:11]
	v_mfma_f32_16x16x32_bf16 v[60:63], v[148:151], v[190:193], v[60:63]
	v_mfma_f32_16x16x32_bf16 v[56:59], v[164:167], v[190:193], v[56:59]
	v_mfma_f32_16x16x32_bf16 v[48:51], v[148:151], v[198:201], v[48:51]
	v_mfma_f32_16x16x32_bf16 v[40:43], v[164:167], v[198:201], v[40:43]
	v_mfma_f32_16x16x32_bf16 v[32:35], v[148:151], v[206:209], v[32:35]
	v_mfma_f32_16x16x32_bf16 v[24:27], v[164:167], v[206:209], v[24:27]
	v_mfma_f32_16x16x32_bf16 v[16:19], v[148:151], v[214:217], v[16:19]
	v_mfma_f32_16x16x32_bf16 v[8:11], v[164:167], v[214:217], v[8:11]
	v_mfma_f32_16x16x32_bf16 v[52:55], v[168:171], v[186:189], v[52:55]
	v_mfma_f32_16x16x32_bf16 v[44:47], v[176:179], v[186:189], v[44:47]
	v_mfma_f32_16x16x32_bf16 v[36:39], v[168:171], v[194:197], v[36:39]
	v_mfma_f32_16x16x32_bf16 v[28:31], v[176:179], v[194:197], v[28:31]
	v_mfma_f32_16x16x32_bf16 v[20:23], v[168:171], v[202:205], v[20:23]
	v_mfma_f32_16x16x32_bf16 v[12:15], v[176:179], v[202:205], v[12:15]
	v_mfma_f32_16x16x32_bf16 v[4:7], v[168:171], v[210:213], v[4:7]
	v_mfma_f32_16x16x32_bf16 v[0:3], v[176:179], v[210:213], v[0:3]
	v_mfma_f32_16x16x32_bf16 v[52:55], v[172:175], v[190:193], v[52:55]
	v_mfma_f32_16x16x32_bf16 v[44:47], v[182:185], v[190:193], v[44:47]
	v_mfma_f32_16x16x32_bf16 v[36:39], v[172:175], v[198:201], v[36:39]
	v_mfma_f32_16x16x32_bf16 v[28:31], v[182:185], v[198:201], v[28:31]
	v_mfma_f32_16x16x32_bf16 v[20:23], v[172:175], v[206:209], v[20:23]
	v_mfma_f32_16x16x32_bf16 v[12:15], v[182:185], v[206:209], v[12:15]
	v_mfma_f32_16x16x32_bf16 v[4:7], v[172:175], v[214:217], v[4:7]
	v_mfma_f32_16x16x32_bf16 v[0:3], v[182:185], v[214:217], v[0:3]
	s_setprio 0
	s_barrier
	s_add_i32 s53, s53, 2
	s_add_u32 s51, s51, 0x100
	s_addc_u32 s52, s52, 0
	s_cmp_gt_u32 s53, 41
	s_mov_b64 s[26:27], s[4:5]
	s_cbranch_scc0 .LBB0_999
	s_and_b64 vcc, exec, s[12:13]
	s_cbranch_vccz .LBB0_1002
	s_barrier
